# write-once GEMM epilogue output stores (P1b q/k/v/gates, P5 h1, P7 act) marked nt so operand streams keep L2/MALL
# baseline (speedup 1.0000x reference)
; #define PG8_GAS __attribute__((address_space(1)))
; __device__ __forceinline__ unsigned cvt_pk_bf16(float lo, float hi) { const f32x2c v = {lo, hi}; return __builtin_bit_cast(unsigned, __builtin_convertvector(v, bf16x2c)); }
; __device__ __forceinline__ float sigmoidf_fast(float x) { return __builtin_amdgcn_rcpf(1.0f + __builtin_amdgcn_exp2f(-1.4426950408889634f * x)); }
;     __device__ __forceinline__ void operator()(const f32x4 (&acc)[2][2][4][2], const Unit& un, int wr, int wc, int fr, int fq) const {
;     ...
;         const int row0 = un.pm * BM + wr * 64 + fr, col0 = ct * BM + wc * 32 + 8 * fq;
; #pragma unroll
;         for (int ai = 0; ai < 2; ++ai)
; #pragma unroll
;             for (int m = 0; m < 4; ++m) { bf16_t* rowp = base + (size_t)(row0 + ai * HALF + m * 16) * ldc + col0;
; #pragma unroll
;                 for (int bj = 0; bj < 2; ++bj) { f32x4 v0 = acc[ai][bj][m][0], v1 = acc[ai][bj][m][1];
;                     if (sg) {
; #pragma unroll
;                         for (int e = 0; e < 4; ++e) { v0[e] = sigmoidf_fast(v0[e]); v1[e] = sigmoidf_fast(v1[e]); } }
;                     u32x4 w; w.x = cvt_pk_bf16(v0[0], v0[1]); w.y = cvt_pk_bf16(v0[2], v0[3]); w.z = cvt_pk_bf16(v1[0], v1[1]); w.w = cvt_pk_bf16(v1[2], v1[3]);
;                     *(PG8_GAS u32x4*)(rowp + bj * HALF) = w; } }
.LBB0_167:
	v_lshl_add_u32 v6, s36, 8, v187
	v_lshl_or_b32 v2, s38, 8, v189
	v_ashrrev_i32_e32 v4, 31, v6
	v_ashrrev_i32_e32 v3, 31, v2
	v_mul_lo_u32 v7, s40, v4
	v_mul_lo_u32 v8, s41, v6
	v_mad_u64_u32 v[4:5], s[36:37], s40, v6, 0
	v_lshl_add_u64 v[2:3], v[2:3], 1, s[42:43]
	v_add3_u32 v5, v5, v7, v8
	v_lshl_add_u64 v[4:5], v[4:5], 1, v[2:3]
	v_cvt_pk_bf16_f32 v8, v158, v159
	v_cvt_pk_bf16_f32 v9, v160, v161
	v_cvt_pk_bf16_f32 v10, v154, v155
	v_cvt_pk_bf16_f32 v11, v156, v157
	s_xor_b64 s[36:37], s[6:7], -1
	global_store_dwordx4 v[4:5], v[8:11], off nt
	s_andn2_b64 vcc, exec, s[36:37]
	s_nop 0
	v_cndmask_b32_e64 v8, 0, 1, s[36:37]
	v_cmp_ne_u32_e64 s[6:7], 1, v8
	s_mov_b64 s[36:37], -1
	s_cbranch_vccnz .LBB0_169
	s_mov_b64 s[36:37], 0

; #define PG8_GAS __attribute__((address_space(1)))
; __device__ __forceinline__ unsigned cvt_pk_bf16(float lo, float hi) { const f32x2c v = {lo, hi}; return __builtin_bit_cast(unsigned, __builtin_convertvector(v, bf16x2c)); }
; __device__ __forceinline__ float sigmoidf_fast(float x) { return __builtin_amdgcn_rcpf(1.0f + __builtin_amdgcn_exp2f(-1.4426950408889634f * x)); }
;     __device__ __forceinline__ void operator()(const f32x4 (&acc)[2][2][4][2], const Unit& un, int wr, int wc, int fr, int fq) const {
;     ...
;             for (int m = 0; m < 4; ++m) { bf16_t* rowp = base + (size_t)(row0 + ai * HALF + m * 16) * ldc + col0;
; #pragma unroll
;                 for (int bj = 0; bj < 2; ++bj) { f32x4 v0 = acc[ai][bj][m][0], v1 = acc[ai][bj][m][1];
;                     if (sg) {
; #pragma unroll
;                         for (int e = 0; e < 4; ++e) { v0[e] = sigmoidf_fast(v0[e]); v1[e] = sigmoidf_fast(v1[e]); } }
;                     u32x4 w; w.x = cvt_pk_bf16(v0[0], v0[1]); w.y = cvt_pk_bf16(v0[2], v0[3]); w.z = cvt_pk_bf16(v1[0], v1[1]); w.w = cvt_pk_bf16(v1[2], v1[3]);
;                     *(PG8_GAS u32x4*)(rowp + bj * HALF) = w; } }
.LBB0_171:
	v_cvt_pk_bf16_f32 v8, v150, v151
	v_cvt_pk_bf16_f32 v9, v152, v153
	v_cvt_pk_bf16_f32 v10, v146, v147
	v_cvt_pk_bf16_f32 v11, v148, v149
	s_and_b64 vcc, exec, s[6:7]
	s_mov_b64 s[36:37], -1
	global_store_dwordx4 v[4:5], v[8:11], off offset:256 nt
	s_cbranch_vccnz .LBB0_173
	s_mov_b64 s[36:37], 0

; #define PG8_GAS __attribute__((address_space(1)))
; __device__ __forceinline__ unsigned cvt_pk_bf16(float lo, float hi) { const f32x2c v = {lo, hi}; return __builtin_bit_cast(unsigned, __builtin_convertvector(v, bf16x2c)); }
; __device__ __forceinline__ float sigmoidf_fast(float x) { return __builtin_amdgcn_rcpf(1.0f + __builtin_amdgcn_exp2f(-1.4426950408889634f * x)); }
;     __device__ __forceinline__ void operator()(const f32x4 (&acc)[2][2][4][2], const Unit& un, int wr, int wc, int fr, int fq) const {
;     ...
;             for (int m = 0; m < 4; ++m) { bf16_t* rowp = base + (size_t)(row0 + ai * HALF + m * 16) * ldc + col0;
; #pragma unroll
;                 for (int bj = 0; bj < 2; ++bj) { f32x4 v0 = acc[ai][bj][m][0], v1 = acc[ai][bj][m][1];
;                     if (sg) {
; #pragma unroll
;                         for (int e = 0; e < 4; ++e) { v0[e] = sigmoidf_fast(v0[e]); v1[e] = sigmoidf_fast(v1[e]); } }
;                     u32x4 w; w.x = cvt_pk_bf16(v0[0], v0[1]); w.y = cvt_pk_bf16(v0[2], v0[3]); w.z = cvt_pk_bf16(v1[0], v1[1]); w.w = cvt_pk_bf16(v1[2], v1[3]);
;                     *(PG8_GAS u32x4*)(rowp + bj * HALF) = w; } }
.LBB0_175:
	v_or_b32_e32 v4, 16, v6
	v_mul_lo_u32 v8, s41, v4
	v_mad_u64_u32 v[4:5], s[36:37], s40, v4, 0
	v_add3_u32 v5, v5, v7, v8
	v_lshl_add_u64 v[4:5], v[4:5], 1, v[2:3]
	v_cvt_pk_bf16_f32 v8, v142, v143
	v_cvt_pk_bf16_f32 v9, v144, v145
	v_cvt_pk_bf16_f32 v10, v138, v139
	v_cvt_pk_bf16_f32 v11, v140, v141
	s_and_b64 vcc, exec, s[6:7]
	s_mov_b64 s[36:37], -1
	global_store_dwordx4 v[4:5], v[8:11], off nt
	s_cbranch_vccnz .LBB0_177
	s_mov_b64 s[36:37], 0

; #define PG8_GAS __attribute__((address_space(1)))
; __device__ __forceinline__ unsigned cvt_pk_bf16(float lo, float hi) { const f32x2c v = {lo, hi}; return __builtin_bit_cast(unsigned, __builtin_convertvector(v, bf16x2c)); }
; __device__ __forceinline__ float sigmoidf_fast(float x) { return __builtin_amdgcn_rcpf(1.0f + __builtin_amdgcn_exp2f(-1.4426950408889634f * x)); }
;     __device__ __forceinline__ void operator()(const f32x4 (&acc)[2][2][4][2], const Unit& un, int wr, int wc, int fr, int fq) const {
;     ...
;             for (int m = 0; m < 4; ++m) { bf16_t* rowp = base + (size_t)(row0 + ai * HALF + m * 16) * ldc + col0;
; #pragma unroll
;                 for (int bj = 0; bj < 2; ++bj) { f32x4 v0 = acc[ai][bj][m][0], v1 = acc[ai][bj][m][1];
;                     if (sg) {
; #pragma unroll
;                         for (int e = 0; e < 4; ++e) { v0[e] = sigmoidf_fast(v0[e]); v1[e] = sigmoidf_fast(v1[e]); } }
;                     u32x4 w; w.x = cvt_pk_bf16(v0[0], v0[1]); w.y = cvt_pk_bf16(v0[2], v0[3]); w.z = cvt_pk_bf16(v1[0], v1[1]); w.w = cvt_pk_bf16(v1[2], v1[3]);
;                     *(PG8_GAS u32x4*)(rowp + bj * HALF) = w; } }
.LBB0_179:
	v_cvt_pk_bf16_f32 v8, v134, v135
	v_cvt_pk_bf16_f32 v9, v136, v137
	v_cvt_pk_bf16_f32 v10, v130, v131
	v_cvt_pk_bf16_f32 v11, v132, v133
	s_and_b64 vcc, exec, s[6:7]
	s_mov_b64 s[36:37], -1
	global_store_dwordx4 v[4:5], v[8:11], off offset:256 nt
	s_cbranch_vccnz .LBB0_181
	s_mov_b64 s[36:37], 0

; #define PG8_GAS __attribute__((address_space(1)))
; __device__ __forceinline__ unsigned cvt_pk_bf16(float lo, float hi) { const f32x2c v = {lo, hi}; return __builtin_bit_cast(unsigned, __builtin_convertvector(v, bf16x2c)); }
; __device__ __forceinline__ float sigmoidf_fast(float x) { return __builtin_amdgcn_rcpf(1.0f + __builtin_amdgcn_exp2f(-1.4426950408889634f * x)); }
;     __device__ __forceinline__ void operator()(const f32x4 (&acc)[2][2][4][2], const Unit& un, int wr, int wc, int fr, int fq) const {
;     ...
;             for (int m = 0; m < 4; ++m) { bf16_t* rowp = base + (size_t)(row0 + ai * HALF + m * 16) * ldc + col0;
; #pragma unroll
;                 for (int bj = 0; bj < 2; ++bj) { f32x4 v0 = acc[ai][bj][m][0], v1 = acc[ai][bj][m][1];
;                     if (sg) {
; #pragma unroll
;                         for (int e = 0; e < 4; ++e) { v0[e] = sigmoidf_fast(v0[e]); v1[e] = sigmoidf_fast(v1[e]); } }
;                     u32x4 w; w.x = cvt_pk_bf16(v0[0], v0[1]); w.y = cvt_pk_bf16(v0[2], v0[3]); w.z = cvt_pk_bf16(v1[0], v1[1]); w.w = cvt_pk_bf16(v1[2], v1[3]);
;                     *(PG8_GAS u32x4*)(rowp + bj * HALF) = w; } }
.LBB0_183:
	v_or_b32_e32 v4, 32, v6
	v_mul_lo_u32 v8, s41, v4
	v_mad_u64_u32 v[4:5], s[36:37], s40, v4, 0
	v_add3_u32 v5, v5, v7, v8
	v_lshl_add_u64 v[4:5], v[4:5], 1, v[2:3]
	v_cvt_pk_bf16_f32 v8, v126, v127
	v_cvt_pk_bf16_f32 v9, v128, v129
	v_cvt_pk_bf16_f32 v10, v122, v123
	v_cvt_pk_bf16_f32 v11, v124, v125
	s_and_b64 vcc, exec, s[6:7]
	s_mov_b64 s[36:37], -1
	global_store_dwordx4 v[4:5], v[8:11], off nt
	s_cbranch_vccnz .LBB0_185
	s_mov_b64 s[36:37], 0

; #define PG8_GAS __attribute__((address_space(1)))
; __device__ __forceinline__ unsigned cvt_pk_bf16(float lo, float hi) { const f32x2c v = {lo, hi}; return __builtin_bit_cast(unsigned, __builtin_convertvector(v, bf16x2c)); }
; __device__ __forceinline__ float sigmoidf_fast(float x) { return __builtin_amdgcn_rcpf(1.0f + __builtin_amdgcn_exp2f(-1.4426950408889634f * x)); }
;     __device__ __forceinline__ void operator()(const f32x4 (&acc)[2][2][4][2], const Unit& un, int wr, int wc, int fr, int fq) const {
;     ...
;             for (int m = 0; m < 4; ++m) { bf16_t* rowp = base + (size_t)(row0 + ai * HALF + m * 16) * ldc + col0;
; #pragma unroll
;                 for (int bj = 0; bj < 2; ++bj) { f32x4 v0 = acc[ai][bj][m][0], v1 = acc[ai][bj][m][1];
;                     if (sg) {
; #pragma unroll
;                         for (int e = 0; e < 4; ++e) { v0[e] = sigmoidf_fast(v0[e]); v1[e] = sigmoidf_fast(v1[e]); } }
;                     u32x4 w; w.x = cvt_pk_bf16(v0[0], v0[1]); w.y = cvt_pk_bf16(v0[2], v0[3]); w.z = cvt_pk_bf16(v1[0], v1[1]); w.w = cvt_pk_bf16(v1[2], v1[3]);
;                     *(PG8_GAS u32x4*)(rowp + bj * HALF) = w; } }
.LBB0_187:
	v_cvt_pk_bf16_f32 v8, v118, v119
	v_cvt_pk_bf16_f32 v9, v120, v121
	v_cvt_pk_bf16_f32 v10, v114, v115
	v_cvt_pk_bf16_f32 v11, v116, v117
	s_and_b64 vcc, exec, s[6:7]
	s_mov_b64 s[36:37], -1
	global_store_dwordx4 v[4:5], v[8:11], off offset:256 nt
	s_cbranch_vccnz .LBB0_189
	s_mov_b64 s[36:37], 0

; #define PG8_GAS __attribute__((address_space(1)))
; __device__ __forceinline__ unsigned cvt_pk_bf16(float lo, float hi) { const f32x2c v = {lo, hi}; return __builtin_bit_cast(unsigned, __builtin_convertvector(v, bf16x2c)); }
; __device__ __forceinline__ float sigmoidf_fast(float x) { return __builtin_amdgcn_rcpf(1.0f + __builtin_amdgcn_exp2f(-1.4426950408889634f * x)); }
;     __device__ __forceinline__ void operator()(const f32x4 (&acc)[2][2][4][2], const Unit& un, int wr, int wc, int fr, int fq) const {
;     ...
;             for (int m = 0; m < 4; ++m) { bf16_t* rowp = base + (size_t)(row0 + ai * HALF + m * 16) * ldc + col0;
; #pragma unroll
;                 for (int bj = 0; bj < 2; ++bj) { f32x4 v0 = acc[ai][bj][m][0], v1 = acc[ai][bj][m][1];
;                     if (sg) {
; #pragma unroll
;                         for (int e = 0; e < 4; ++e) { v0[e] = sigmoidf_fast(v0[e]); v1[e] = sigmoidf_fast(v1[e]); } }
;                     u32x4 w; w.x = cvt_pk_bf16(v0[0], v0[1]); w.y = cvt_pk_bf16(v0[2], v0[3]); w.z = cvt_pk_bf16(v1[0], v1[1]); w.w = cvt_pk_bf16(v1[2], v1[3]);
;                     *(PG8_GAS u32x4*)(rowp + bj * HALF) = w; } }
.LBB0_191:
	v_or_b32_e32 v4, 48, v6
	v_mul_lo_u32 v8, s41, v4
	v_mad_u64_u32 v[4:5], s[36:37], s40, v4, 0
	v_add3_u32 v5, v5, v7, v8
	v_lshl_add_u64 v[4:5], v[4:5], 1, v[2:3]
	v_cvt_pk_bf16_f32 v8, v110, v111
	v_cvt_pk_bf16_f32 v9, v112, v113
	v_cvt_pk_bf16_f32 v10, v106, v107
	v_cvt_pk_bf16_f32 v11, v108, v109
	s_and_b64 vcc, exec, s[6:7]
	s_mov_b64 s[36:37], -1
	global_store_dwordx4 v[4:5], v[8:11], off nt
	s_cbranch_vccnz .LBB0_193
	s_mov_b64 s[36:37], 0

; #define PG8_GAS __attribute__((address_space(1)))
; __device__ __forceinline__ unsigned cvt_pk_bf16(float lo, float hi) { const f32x2c v = {lo, hi}; return __builtin_bit_cast(unsigned, __builtin_convertvector(v, bf16x2c)); }
; __device__ __forceinline__ float sigmoidf_fast(float x) { return __builtin_amdgcn_rcpf(1.0f + __builtin_amdgcn_exp2f(-1.4426950408889634f * x)); }
;     __device__ __forceinline__ void operator()(const f32x4 (&acc)[2][2][4][2], const Unit& un, int wr, int wc, int fr, int fq) const {
;     ...
;             for (int m = 0; m < 4; ++m) { bf16_t* rowp = base + (size_t)(row0 + ai * HALF + m * 16) * ldc + col0;
; #pragma unroll
;                 for (int bj = 0; bj < 2; ++bj) { f32x4 v0 = acc[ai][bj][m][0], v1 = acc[ai][bj][m][1];
;                     if (sg) {
; #pragma unroll
;                         for (int e = 0; e < 4; ++e) { v0[e] = sigmoidf_fast(v0[e]); v1[e] = sigmoidf_fast(v1[e]); } }
;                     u32x4 w; w.x = cvt_pk_bf16(v0[0], v0[1]); w.y = cvt_pk_bf16(v0[2], v0[3]); w.z = cvt_pk_bf16(v1[0], v1[1]); w.w = cvt_pk_bf16(v1[2], v1[3]);
;                     *(PG8_GAS u32x4*)(rowp + bj * HALF) = w; } }
.LBB0_195:
	v_cvt_pk_bf16_f32 v8, v102, v103
	v_cvt_pk_bf16_f32 v9, v104, v105
	v_cvt_pk_bf16_f32 v10, v98, v99
	v_cvt_pk_bf16_f32 v11, v100, v101
	s_and_b64 vcc, exec, s[6:7]
	s_mov_b64 s[36:37], -1
	global_store_dwordx4 v[4:5], v[8:11], off offset:256 nt
	s_cbranch_vccnz .LBB0_197
	s_mov_b64 s[36:37], 0

; #define PG8_GAS __attribute__((address_space(1)))
; __device__ __forceinline__ unsigned cvt_pk_bf16(float lo, float hi) { const f32x2c v = {lo, hi}; return __builtin_bit_cast(unsigned, __builtin_convertvector(v, bf16x2c)); }
; __device__ __forceinline__ float sigmoidf_fast(float x) { return __builtin_amdgcn_rcpf(1.0f + __builtin_amdgcn_exp2f(-1.4426950408889634f * x)); }
;     __device__ __forceinline__ void operator()(const f32x4 (&acc)[2][2][4][2], const Unit& un, int wr, int wc, int fr, int fq) const {
;     ...
;             for (int m = 0; m < 4; ++m) { bf16_t* rowp = base + (size_t)(row0 + ai * HALF + m * 16) * ldc + col0;
; #pragma unroll
;                 for (int bj = 0; bj < 2; ++bj) { f32x4 v0 = acc[ai][bj][m][0], v1 = acc[ai][bj][m][1];
;                     if (sg) {
; #pragma unroll
;                         for (int e = 0; e < 4; ++e) { v0[e] = sigmoidf_fast(v0[e]); v1[e] = sigmoidf_fast(v1[e]); } }
;                     u32x4 w; w.x = cvt_pk_bf16(v0[0], v0[1]); w.y = cvt_pk_bf16(v0[2], v0[3]); w.z = cvt_pk_bf16(v1[0], v1[1]); w.w = cvt_pk_bf16(v1[2], v1[3]);
;                     *(PG8_GAS u32x4*)(rowp + bj * HALF) = w; } }
.LBB0_199:
	v_add_u32_e32 v4, 0x80, v6
	v_ashrrev_i32_e32 v5, 31, v4
	v_mul_lo_u32 v7, s40, v5
	v_mul_lo_u32 v8, s41, v4
	v_mad_u64_u32 v[4:5], s[36:37], s40, v4, 0
	v_add3_u32 v5, v5, v7, v8
	v_lshl_add_u64 v[4:5], v[4:5], 1, v[2:3]
	v_cvt_pk_bf16_f32 v8, v94, v95
	v_cvt_pk_bf16_f32 v9, v96, v97
	v_cvt_pk_bf16_f32 v10, v90, v91
	v_cvt_pk_bf16_f32 v11, v92, v93
	s_and_b64 vcc, exec, s[6:7]
	s_mov_b64 s[36:37], -1
	global_store_dwordx4 v[4:5], v[8:11], off nt
	s_cbranch_vccnz .LBB0_201
	s_mov_b64 s[36:37], 0

; #define PG8_GAS __attribute__((address_space(1)))
; __device__ __forceinline__ unsigned cvt_pk_bf16(float lo, float hi) { const f32x2c v = {lo, hi}; return __builtin_bit_cast(unsigned, __builtin_convertvector(v, bf16x2c)); }
; __device__ __forceinline__ float sigmoidf_fast(float x) { return __builtin_amdgcn_rcpf(1.0f + __builtin_amdgcn_exp2f(-1.4426950408889634f * x)); }
;     __device__ __forceinline__ void operator()(const f32x4 (&acc)[2][2][4][2], const Unit& un, int wr, int wc, int fr, int fq) const {
;     ...
;             for (int m = 0; m < 4; ++m) { bf16_t* rowp = base + (size_t)(row0 + ai * HALF + m * 16) * ldc + col0;
; #pragma unroll
;                 for (int bj = 0; bj < 2; ++bj) { f32x4 v0 = acc[ai][bj][m][0], v1 = acc[ai][bj][m][1];
;                     if (sg) {
; #pragma unroll
;                         for (int e = 0; e < 4; ++e) { v0[e] = sigmoidf_fast(v0[e]); v1[e] = sigmoidf_fast(v1[e]); } }
;                     u32x4 w; w.x = cvt_pk_bf16(v0[0], v0[1]); w.y = cvt_pk_bf16(v0[2], v0[3]); w.z = cvt_pk_bf16(v1[0], v1[1]); w.w = cvt_pk_bf16(v1[2], v1[3]);
;                     *(PG8_GAS u32x4*)(rowp + bj * HALF) = w; } }
.LBB0_203:
	v_cvt_pk_bf16_f32 v8, v86, v87
	v_cvt_pk_bf16_f32 v9, v88, v89
	v_cvt_pk_bf16_f32 v10, v82, v83
	v_cvt_pk_bf16_f32 v11, v84, v85
	s_and_b64 vcc, exec, s[6:7]
	s_mov_b64 s[36:37], -1
	global_store_dwordx4 v[4:5], v[8:11], off offset:256 nt
	s_cbranch_vccnz .LBB0_205
	s_mov_b64 s[36:37], 0

; #define PG8_GAS __attribute__((address_space(1)))
; __device__ __forceinline__ unsigned cvt_pk_bf16(float lo, float hi) { const f32x2c v = {lo, hi}; return __builtin_bit_cast(unsigned, __builtin_convertvector(v, bf16x2c)); }
; __device__ __forceinline__ float sigmoidf_fast(float x) { return __builtin_amdgcn_rcpf(1.0f + __builtin_amdgcn_exp2f(-1.4426950408889634f * x)); }
;     __device__ __forceinline__ void operator()(const f32x4 (&acc)[2][2][4][2], const Unit& un, int wr, int wc, int fr, int fq) const {
;     ...
;             for (int m = 0; m < 4; ++m) { bf16_t* rowp = base + (size_t)(row0 + ai * HALF + m * 16) * ldc + col0;
; #pragma unroll
;                 for (int bj = 0; bj < 2; ++bj) { f32x4 v0 = acc[ai][bj][m][0], v1 = acc[ai][bj][m][1];
;                     if (sg) {
; #pragma unroll
;                         for (int e = 0; e < 4; ++e) { v0[e] = sigmoidf_fast(v0[e]); v1[e] = sigmoidf_fast(v1[e]); } }
;                     u32x4 w; w.x = cvt_pk_bf16(v0[0], v0[1]); w.y = cvt_pk_bf16(v0[2], v0[3]); w.z = cvt_pk_bf16(v1[0], v1[1]); w.w = cvt_pk_bf16(v1[2], v1[3]);
;                     *(PG8_GAS u32x4*)(rowp + bj * HALF) = w; } }
.LBB0_207:
	v_add_u32_e32 v4, 0x90, v6
	v_ashrrev_i32_e32 v5, 31, v4
	v_mul_lo_u32 v7, s40, v5
	v_mul_lo_u32 v8, s41, v4
	v_mad_u64_u32 v[4:5], s[36:37], s40, v4, 0
	v_add3_u32 v5, v5, v7, v8
	v_lshl_add_u64 v[4:5], v[4:5], 1, v[2:3]
	v_cvt_pk_bf16_f32 v8, v78, v79
	v_cvt_pk_bf16_f32 v9, v80, v81
	v_cvt_pk_bf16_f32 v10, v74, v75
	v_cvt_pk_bf16_f32 v11, v76, v77
	s_and_b64 vcc, exec, s[6:7]
	s_mov_b64 s[36:37], -1
	global_store_dwordx4 v[4:5], v[8:11], off nt
	s_cbranch_vccnz .LBB0_209
	s_mov_b64 s[36:37], 0

; #define PG8_GAS __attribute__((address_space(1)))
; __device__ __forceinline__ unsigned cvt_pk_bf16(float lo, float hi) { const f32x2c v = {lo, hi}; return __builtin_bit_cast(unsigned, __builtin_convertvector(v, bf16x2c)); }
; __device__ __forceinline__ float sigmoidf_fast(float x) { return __builtin_amdgcn_rcpf(1.0f + __builtin_amdgcn_exp2f(-1.4426950408889634f * x)); }
;     __device__ __forceinline__ void operator()(const f32x4 (&acc)[2][2][4][2], const Unit& un, int wr, int wc, int fr, int fq) const {
;     ...
;             for (int m = 0; m < 4; ++m) { bf16_t* rowp = base + (size_t)(row0 + ai * HALF + m * 16) * ldc + col0;
; #pragma unroll
;                 for (int bj = 0; bj < 2; ++bj) { f32x4 v0 = acc[ai][bj][m][0], v1 = acc[ai][bj][m][1];
;                     if (sg) {
; #pragma unroll
;                         for (int e = 0; e < 4; ++e) { v0[e] = sigmoidf_fast(v0[e]); v1[e] = sigmoidf_fast(v1[e]); } }
;                     u32x4 w; w.x = cvt_pk_bf16(v0[0], v0[1]); w.y = cvt_pk_bf16(v0[2], v0[3]); w.z = cvt_pk_bf16(v1[0], v1[1]); w.w = cvt_pk_bf16(v1[2], v1[3]);
;                     *(PG8_GAS u32x4*)(rowp + bj * HALF) = w; } }
.LBB0_211:
	v_cvt_pk_bf16_f32 v8, v70, v71
	v_cvt_pk_bf16_f32 v9, v72, v73
	v_cvt_pk_bf16_f32 v10, v66, v67
	v_cvt_pk_bf16_f32 v11, v68, v69
	s_and_b64 vcc, exec, s[6:7]
	s_mov_b64 s[36:37], -1
	global_store_dwordx4 v[4:5], v[8:11], off offset:256 nt
	s_cbranch_vccnz .LBB0_213
	s_mov_b64 s[36:37], 0

; #define PG8_GAS __attribute__((address_space(1)))
; __device__ __forceinline__ unsigned cvt_pk_bf16(float lo, float hi) { const f32x2c v = {lo, hi}; return __builtin_bit_cast(unsigned, __builtin_convertvector(v, bf16x2c)); }
; __device__ __forceinline__ float sigmoidf_fast(float x) { return __builtin_amdgcn_rcpf(1.0f + __builtin_amdgcn_exp2f(-1.4426950408889634f * x)); }
;     __device__ __forceinline__ void operator()(const f32x4 (&acc)[2][2][4][2], const Unit& un, int wr, int wc, int fr, int fq) const {
;     ...
;             for (int m = 0; m < 4; ++m) { bf16_t* rowp = base + (size_t)(row0 + ai * HALF + m * 16) * ldc + col0;
; #pragma unroll
;                 for (int bj = 0; bj < 2; ++bj) { f32x4 v0 = acc[ai][bj][m][0], v1 = acc[ai][bj][m][1];
;                     if (sg) {
; #pragma unroll
;                         for (int e = 0; e < 4; ++e) { v0[e] = sigmoidf_fast(v0[e]); v1[e] = sigmoidf_fast(v1[e]); } }
;                     u32x4 w; w.x = cvt_pk_bf16(v0[0], v0[1]); w.y = cvt_pk_bf16(v0[2], v0[3]); w.z = cvt_pk_bf16(v1[0], v1[1]); w.w = cvt_pk_bf16(v1[2], v1[3]);
;                     *(PG8_GAS u32x4*)(rowp + bj * HALF) = w; } }
.LBB0_215:
	v_add_u32_e32 v4, 0xa0, v6
	v_ashrrev_i32_e32 v5, 31, v4
	v_mul_lo_u32 v7, s40, v5
	v_mul_lo_u32 v8, s41, v4
	v_mad_u64_u32 v[4:5], s[36:37], s40, v4, 0
	v_add3_u32 v5, v5, v7, v8
	v_lshl_add_u64 v[4:5], v[4:5], 1, v[2:3]
	v_cvt_pk_bf16_f32 v8, v62, v63
	v_cvt_pk_bf16_f32 v9, v64, v65
	v_cvt_pk_bf16_f32 v10, v58, v59
	v_cvt_pk_bf16_f32 v11, v60, v61
	s_and_b64 vcc, exec, s[6:7]
	s_mov_b64 s[36:37], -1
	global_store_dwordx4 v[4:5], v[8:11], off nt
	s_cbranch_vccnz .LBB0_217
	s_mov_b64 s[36:37], 0

; #define PG8_GAS __attribute__((address_space(1)))
; __device__ __forceinline__ unsigned cvt_pk_bf16(float lo, float hi) { const f32x2c v = {lo, hi}; return __builtin_bit_cast(unsigned, __builtin_convertvector(v, bf16x2c)); }
; __device__ __forceinline__ float sigmoidf_fast(float x) { return __builtin_amdgcn_rcpf(1.0f + __builtin_amdgcn_exp2f(-1.4426950408889634f * x)); }
;     __device__ __forceinline__ void operator()(const f32x4 (&acc)[2][2][4][2], const Unit& un, int wr, int wc, int fr, int fq) const {
;     ...
;             for (int m = 0; m < 4; ++m) { bf16_t* rowp = base + (size_t)(row0 + ai * HALF + m * 16) * ldc + col0;
; #pragma unroll
;                 for (int bj = 0; bj < 2; ++bj) { f32x4 v0 = acc[ai][bj][m][0], v1 = acc[ai][bj][m][1];
;                     if (sg) {
; #pragma unroll
;                         for (int e = 0; e < 4; ++e) { v0[e] = sigmoidf_fast(v0[e]); v1[e] = sigmoidf_fast(v1[e]); } }
;                     u32x4 w; w.x = cvt_pk_bf16(v0[0], v0[1]); w.y = cvt_pk_bf16(v0[2], v0[3]); w.z = cvt_pk_bf16(v1[0], v1[1]); w.w = cvt_pk_bf16(v1[2], v1[3]);
;                     *(PG8_GAS u32x4*)(rowp + bj * HALF) = w; } }
.LBB0_219:
	v_cvt_pk_bf16_f32 v8, v54, v55
	v_cvt_pk_bf16_f32 v9, v56, v57
	v_cvt_pk_bf16_f32 v10, v50, v51
	v_cvt_pk_bf16_f32 v11, v52, v53
	s_and_b64 vcc, exec, s[6:7]
	s_mov_b64 s[36:37], -1
	global_store_dwordx4 v[4:5], v[8:11], off offset:256 nt
	s_cbranch_vccnz .LBB0_221
	s_mov_b64 s[36:37], 0

; #define PG8_GAS __attribute__((address_space(1)))
; __device__ __forceinline__ unsigned cvt_pk_bf16(float lo, float hi) { const f32x2c v = {lo, hi}; return __builtin_bit_cast(unsigned, __builtin_convertvector(v, bf16x2c)); }
; __device__ __forceinline__ float sigmoidf_fast(float x) { return __builtin_amdgcn_rcpf(1.0f + __builtin_amdgcn_exp2f(-1.4426950408889634f * x)); }
;     __device__ __forceinline__ void operator()(const f32x4 (&acc)[2][2][4][2], const Unit& un, int wr, int wc, int fr, int fq) const {
;     ...
;             for (int m = 0; m < 4; ++m) { bf16_t* rowp = base + (size_t)(row0 + ai * HALF + m * 16) * ldc + col0;
; #pragma unroll
;                 for (int bj = 0; bj < 2; ++bj) { f32x4 v0 = acc[ai][bj][m][0], v1 = acc[ai][bj][m][1];
;                     if (sg) {
; #pragma unroll
;                         for (int e = 0; e < 4; ++e) { v0[e] = sigmoidf_fast(v0[e]); v1[e] = sigmoidf_fast(v1[e]); } }
;                     u32x4 w; w.x = cvt_pk_bf16(v0[0], v0[1]); w.y = cvt_pk_bf16(v0[2], v0[3]); w.z = cvt_pk_bf16(v1[0], v1[1]); w.w = cvt_pk_bf16(v1[2], v1[3]);
;                     *(PG8_GAS u32x4*)(rowp + bj * HALF) = w; } }
.LBB0_223:
	v_add_u32_e32 v4, 0xb0, v6
	v_ashrrev_i32_e32 v5, 31, v4
	v_mul_lo_u32 v6, s40, v5
	v_mul_lo_u32 v7, s41, v4
	v_mad_u64_u32 v[4:5], s[36:37], s40, v4, 0
	v_add3_u32 v5, v5, v6, v7
	v_lshl_add_u64 v[2:3], v[4:5], 1, v[2:3]
	v_cvt_pk_bf16_f32 v4, v46, v47
	v_cvt_pk_bf16_f32 v5, v48, v49
	v_cvt_pk_bf16_f32 v6, v42, v43
	v_cvt_pk_bf16_f32 v7, v44, v45
	s_and_b64 vcc, exec, s[6:7]
	s_mov_b64 s[6:7], -1
	global_store_dwordx4 v[2:3], v[4:7], off nt
	s_cbranch_vccnz .LBB0_225
	s_mov_b64 s[6:7], 0

; #define PG8_GAS __attribute__((address_space(1)))
; __device__ __forceinline__ unsigned cvt_pk_bf16(float lo, float hi) { const f32x2c v = {lo, hi}; return __builtin_bit_cast(unsigned, __builtin_convertvector(v, bf16x2c)); }
; __device__ __forceinline__ float sigmoidf_fast(float x) { return __builtin_amdgcn_rcpf(1.0f + __builtin_amdgcn_exp2f(-1.4426950408889634f * x)); }
; #define PG8_BAR __builtin_amdgcn_s_barrier()
;     __device__ __forceinline__ void operator()(const f32x4 (&acc)[2][2][4][2], const Unit& un, int wr, int wc, int fr, int fq) const {
;     ...
;             for (int m = 0; m < 4; ++m) { bf16_t* rowp = base + (size_t)(row0 + ai * HALF + m * 16) * ldc + col0;
; #pragma unroll
;                 for (int bj = 0; bj < 2; ++bj) { f32x4 v0 = acc[ai][bj][m][0], v1 = acc[ai][bj][m][1];
;                     if (sg) {
; #pragma unroll
;                         for (int e = 0; e < 4; ++e) { v0[e] = sigmoidf_fast(v0[e]); v1[e] = sigmoidf_fast(v1[e]); } }
;                     u32x4 w; w.x = cvt_pk_bf16(v0[0], v0[1]); w.y = cvt_pk_bf16(v0[2], v0[3]); w.z = cvt_pk_bf16(v1[0], v1[1]); w.w = cvt_pk_bf16(v1[2], v1[3]);
;                     *(PG8_GAS u32x4*)(rowp + bj * HALF) = w; } }
; template <class Epi, class Sched, bool ALIGN_EPI = false, bool SP2 = false, bool F8 = false>
; __device__ __forceinline__ void gemm_phase(PG8_LAS unsigned char* lds, const Gemm g, const Sched& S, const Epi& E) {
;     ...
;         if (!has_next) break;
; #pragma unroll
;         for (int a = 0; a < 2; ++a)
; #pragma unroll
;             for (int b = 0; b < 2; ++b)
; #pragma unroll
;                 for (int m = 0; m < 4; ++m)
; #pragma unroll
;                     for (int n = 0; n < 2; ++n) acc[a][b][m][n] = (f32x4){0.f, 0.f, 0.f, 0.f};
;         cur = nxt; cA = nA; cB = nB; ++ui;
;         if constexpr (ALIGN_EPI) { if (wr == 1) PG8_BAR; }
.LBB0_227:
	v_cvt_pk_bf16_f32 v4, v38, v39
	v_cvt_pk_bf16_f32 v5, v40, v41
	v_cvt_pk_bf16_f32 v6, v34, v35
	v_cvt_pk_bf16_f32 v7, v36, v37
	s_andn2_b64 vcc, exec, s[4:5]
	s_mov_b64 s[4:5], -1
	global_store_dwordx4 v[2:3], v[4:7], off offset:256 nt
	s_cbranch_vccnz .LBB0_142
	s_andn2_b64 vcc, exec, s[8:9]
	s_cbranch_vccnz .LBB0_141
	s_barrier
	s_branch .LBB0_141

; #define PG8_GAS __attribute__((address_space(1)))
; __device__ __forceinline__ unsigned cvt_pk_bf16(float lo, float hi) { const f32x2c v = {lo, hi}; return __builtin_bit_cast(unsigned, __builtin_convertvector(v, bf16x2c)); }
;     __device__ __forceinline__ void run(const f32x4 (&acc)[2][2][4][2], const Unit& un, int wr, int wc, int fr, int fq, PG8_LAS unsigned char* xl) const {
;     ...
; #pragma unroll
;         for (int ai = 0; ai < 2; ++ai) {
;             f32x4 bb[4][2][2];
; #pragma unroll
;             for (int m = 0; m < 4; ++m)
; #pragma unroll
;                 for (int bj = 0; bj < 2; ++bj)
; #pragma unroll
;                     for (int n = 0; n < 2; ++n) bb[m][bj][n] = *(const PG8_GAS f32x4*)(bs + (size_t)(rloc + ai * HALF + m * 16) * 4096 + col0 + bj * HALF + 4 * n);
;             asm volatile("" ::: "memory");
; #pragma unroll
;             for (int m = 0; m < 4; ++m) { float s = 0.f;
; #pragma unroll
;                 for (int bj = 0; bj < 2; ++bj) { const f32x4 h0 = bb[m][bj][0] + acc[ai][bj][m][0], h1 = bb[m][bj][1] + acc[ai][bj][m][1];
;                     s += ((h0[0] * h0[0] + h0[1] * h0[1]) + (h0[2] * h0[2] + h0[3] * h0[3])) + ((h1[0] * h1[0] + h1[1] * h1[1]) + (h1[2] * h1[2] + h1[3] * h1[3]));
;                     u32x4 w; w.x = cvt_pk_bf16(h0[0], h0[1]); w.y = cvt_pk_bf16(h0[2], h0[3]); w.z = cvt_pk_bf16(h1[0], h1[1]); w.w = cvt_pk_bf16(h1[2], h1[3]);
;                     *(PG8_GAS u32x4*)(hs + (size_t)(rloc + ai * HALF + m * 16) * 4096 + col0 + bj * HALF) = w; }
;                 s += __shfl_xor(s, 16); s += __shfl_xor(s, 32);
;                 if (fq == 0) X[wc * 256 + rloc + ai * HALF + m * 16] = s; }
.LBB0_694:
	v_add_u32_e32 v198, s49, v214
	v_lshl_or_b32 v194, s34, 8, v208
	v_ashrrev_i32_e32 v195, 31, v194
	v_ashrrev_i32_e32 v199, 31, v198
	v_lshl_add_u64 v[196:197], v[194:195], 2, s[36:37]
	v_lshlrev_b64 v[130:131], 14, v[198:199]
	v_lshl_add_u64 v[130:131], v[196:197], 0, v[130:131]
	global_load_dwordx4 v[218:221], v[130:131], off
	global_load_dwordx4 v[222:225], v[130:131], off offset:16
	global_load_dwordx4 v[226:229], v[130:131], off offset:512
	global_load_dwordx4 v[230:233], v[130:131], off offset:528
	v_add_u32_e32 v204, 16, v198
	v_add_u32_e32 v202, 32, v198
	v_add_u32_e32 v200, 48, v198
	v_ashrrev_i32_e32 v205, 31, v204
	v_ashrrev_i32_e32 v203, 31, v202
	v_ashrrev_i32_e32 v201, 31, v200
	v_lshlrev_b64 v[130:131], 14, v[204:205]
	v_lshlrev_b64 v[132:133], 14, v[202:203]
	v_lshlrev_b64 v[134:135], 14, v[200:201]
	v_lshl_add_u64 v[130:131], v[196:197], 0, v[130:131]
	v_lshl_add_u64 v[132:133], v[196:197], 0, v[132:133]
	v_lshl_add_u64 v[134:135], v[196:197], 0, v[134:135]
	global_load_dwordx4 v[170:173], v[130:131], off offset:16
	global_load_dwordx4 v[174:177], v[130:131], off
	global_load_dwordx4 v[162:165], v[130:131], off offset:528
	global_load_dwordx4 v[166:169], v[130:131], off offset:512
	global_load_dwordx4 v[154:157], v[132:133], off offset:16
	global_load_dwordx4 v[158:161], v[132:133], off
	global_load_dwordx4 v[146:149], v[132:133], off offset:528
	global_load_dwordx4 v[150:153], v[132:133], off offset:512
	global_load_dwordx4 v[138:141], v[134:135], off offset:16
	global_load_dwordx4 v[142:145], v[134:135], off
	s_nop 0
	global_load_dwordx4 v[130:133], v[134:135], off offset:528
	s_nop 0
	global_load_dwordx4 v[134:137], v[134:135], off offset:512
	v_and_b32_e32 v217, 64, v213
	v_xor_b32_e32 v216, 16, v213
	v_add_u32_e32 v217, 64, v217
	v_xor_b32_e32 v234, 32, v213
	v_cmp_lt_i32_e32 vcc, v216, v217
	s_lshl_b64 s[34:35], s[16:17], 21
	s_add_u32 s34, s45, s34
	v_cndmask_b32_e32 v216, v213, v216, vcc
	v_cmp_lt_i32_e32 vcc, v234, v217
	v_lshlrev_b32_e32 v216, 2, v216
	s_addc_u32 s35, s46, s35
	v_cndmask_b32_e32 v217, v213, v234, vcc
	v_lshlrev_b64 v[234:235], 13, v[198:199]
	v_lshlrev_b32_e32 v199, 2, v217
	v_lshl_add_u64 v[194:195], v[194:195], 1, s[34:35]
	v_lshl_add_u64 v[234:235], v[194:195], 0, v[234:235]
	v_lshl_add_u32 v215, v198, 2, s52
	s_waitcnt vmcnt(0)
	v_pk_add_f32 v[128:129], v[128:129], v[220:221]
	v_pk_add_f32 v[126:127], v[126:127], v[218:219]
	v_pk_add_f32 v[124:125], v[124:125], v[224:225]
	v_pk_add_f32 v[122:123], v[122:123], v[222:223]
	v_pk_add_f32 v[120:121], v[120:121], v[228:229]
	v_pk_add_f32 v[118:119], v[118:119], v[226:227]
	v_pk_add_f32 v[218:219], v[116:117], v[232:233]
	v_pk_add_f32 v[220:221], v[114:115], v[230:231]
	v_mul_f32_e32 v116, v127, v127
	v_mul_f32_e32 v117, v129, v129
	v_mul_f32_e32 v217, v123, v123
	v_mul_f32_e32 v222, v125, v125
	v_cvt_pk_bf16_f32 v114, v126, v127
	v_cvt_pk_bf16_f32 v115, v128, v129
	v_mul_f32_e32 v127, v119, v119
	v_mul_f32_e32 v129, v121, v121
	v_mul_f32_e32 v223, v221, v221
	v_mul_f32_e32 v224, v219, v219
	v_fmac_f32_e32 v116, v126, v126
	v_fmac_f32_e32 v117, v128, v128
	v_fmac_f32_e32 v217, v122, v122
	v_fmac_f32_e32 v222, v124, v124
	v_fmac_f32_e32 v127, v118, v118
	v_fmac_f32_e32 v129, v120, v120
	v_fmac_f32_e32 v223, v220, v220
	v_fmac_f32_e32 v224, v218, v218
	v_add_f32_e32 v116, v116, v117
	v_add_f32_e32 v117, v217, v222
	v_add_f32_e32 v126, v127, v129
	v_add_f32_e32 v127, v223, v224
	v_add_f32_e32 v116, v116, v117
	v_add_f32_e32 v117, v126, v127
	v_add_f32_e32 v126, v116, v117
	ds_bpermute_b32 v127, v216, v126
	v_cvt_pk_bf16_f32 v116, v122, v123
	v_cvt_pk_bf16_f32 v117, v124, v125
	global_store_dwordx4 v[234:235], v[114:117], off nt
	s_waitcnt lgkmcnt(0)
	s_nop 0
	v_add_f32_e32 v114, v126, v127
	ds_bpermute_b32 v115, v199, v114
	v_cvt_pk_bf16_f32 v116, v118, v119
	v_cvt_pk_bf16_f32 v117, v120, v121
	v_cvt_pk_bf16_f32 v118, v220, v221
	v_cvt_pk_bf16_f32 v119, v218, v219
	global_store_dwordx4 v[234:235], v[116:119], off offset:256 nt
	s_and_saveexec_b64 s[34:35], s[8:9]
	s_cbranch_execz .LBB0_696
	s_waitcnt lgkmcnt(0)
	v_add_f32_e32 v114, v114, v115
	ds_write_b32 v215, v114
.LBB0_696:
	s_or_b64 exec, exec, s[34:35]
	v_pk_add_f32 v[112:113], v[112:113], v[176:177]
	v_pk_add_f32 v[110:111], v[110:111], v[174:175]
	v_pk_add_f32 v[116:117], v[108:109], v[172:173]
	v_pk_add_f32 v[108:109], v[106:107], v[170:171]
	v_mul_f32_e32 v106, v111, v111
	v_mul_f32_e32 v107, v113, v113
	v_fmac_f32_e32 v106, v110, v110
	v_fmac_f32_e32 v107, v112, v112
	v_add_f32_e32 v106, v106, v107
	v_mul_f32_e32 v107, v109, v109
	v_mul_f32_e32 v118, v117, v117
	v_fmac_f32_e32 v107, v108, v108
	v_fmac_f32_e32 v118, v116, v116
	v_add_f32_e32 v107, v107, v118
	v_pk_add_f32 v[104:105], v[104:105], v[168:169]
	v_pk_add_f32 v[102:103], v[102:103], v[166:167]
	v_add_f32_e32 v118, v106, v107
	v_cvt_pk_bf16_f32 v107, v112, v113
	v_pk_add_f32 v[112:113], v[98:99], v[162:163]
	v_mul_f32_e32 v98, v103, v103
	v_mul_f32_e32 v99, v105, v105
	v_cvt_pk_bf16_f32 v106, v110, v111
	v_pk_add_f32 v[110:111], v[100:101], v[164:165]
	v_fmac_f32_e32 v98, v102, v102
	v_fmac_f32_e32 v99, v104, v104
	v_add_f32_e32 v98, v98, v99
	v_mul_f32_e32 v99, v113, v113
	v_mul_f32_e32 v100, v111, v111
	v_fmac_f32_e32 v99, v112, v112
	v_fmac_f32_e32 v100, v110, v110
	v_add_f32_e32 v99, v99, v100
	v_add_f32_e32 v98, v98, v99
	v_add_f32_e32 v98, v118, v98
	ds_bpermute_b32 v99, v216, v98
	s_waitcnt lgkmcnt(1)
	v_lshlrev_b64 v[114:115], 13, v[204:205]
	v_lshl_add_u64 v[114:115], v[194:195], 0, v[114:115]
	v_cvt_pk_bf16_f32 v108, v108, v109
	v_cvt_pk_bf16_f32 v109, v116, v117
	s_waitcnt lgkmcnt(0)
	v_add_f32_e32 v98, v98, v99
	ds_bpermute_b32 v99, v199, v98
	v_cvt_pk_bf16_f32 v100, v102, v103
	v_cvt_pk_bf16_f32 v101, v104, v105
	v_cvt_pk_bf16_f32 v102, v112, v113
	v_cvt_pk_bf16_f32 v103, v110, v111
	global_store_dwordx4 v[114:115], v[106:109], off nt
	global_store_dwordx4 v[114:115], v[100:103], off offset:256 nt
	s_and_saveexec_b64 s[34:35], s[8:9]
	s_cbranch_execz .LBB0_698
	s_waitcnt lgkmcnt(0)
	v_add_f32_e32 v98, v98, v99
	ds_write_b32 v215, v98 offset:64
; #define PG8_GAS __attribute__((address_space(1)))
; __device__ __forceinline__ unsigned cvt_pk_bf16(float lo, float hi) { const f32x2c v = {lo, hi}; return __builtin_bit_cast(unsigned, __builtin_convertvector(v, bf16x2c)); }
;     __device__ __forceinline__ void run(const f32x4 (&acc)[2][2][4][2], const Unit& un, int wr, int wc, int fr, int fq, PG8_LAS unsigned char* xl) const {
;     ...
;             for (int m = 0; m < 4; ++m)
; #pragma unroll
;                 for (int bj = 0; bj < 2; ++bj)
; #pragma unroll
;                     for (int n = 0; n < 2; ++n) bb[m][bj][n] = *(const PG8_GAS f32x4*)(bs + (size_t)(rloc + ai * HALF + m * 16) * 4096 + col0 + bj * HALF + 4 * n);
;             asm volatile("" ::: "memory");
; #pragma unroll
;             for (int m = 0; m < 4; ++m) { float s = 0.f;
; #pragma unroll
;                 for (int bj = 0; bj < 2; ++bj) { const f32x4 h0 = bb[m][bj][0] + acc[ai][bj][m][0], h1 = bb[m][bj][1] + acc[ai][bj][m][1];
;                     s += ((h0[0] * h0[0] + h0[1] * h0[1]) + (h0[2] * h0[2] + h0[3] * h0[3])) + ((h1[0] * h1[0] + h1[1] * h1[1]) + (h1[2] * h1[2] + h1[3] * h1[3]));
;                     u32x4 w; w.x = cvt_pk_bf16(h0[0], h0[1]); w.y = cvt_pk_bf16(h0[2], h0[3]); w.z = cvt_pk_bf16(h1[0], h1[1]); w.w = cvt_pk_bf16(h1[2], h1[3]);
;                     *(PG8_GAS u32x4*)(hs + (size_t)(rloc + ai * HALF + m * 16) * 4096 + col0 + bj * HALF) = w; }
;                 s += __shfl_xor(s, 16); s += __shfl_xor(s, 32);
;                 if (fq == 0) X[wc * 256 + rloc + ai * HALF + m * 16] = s; }
.LBB0_698:
	s_or_b64 exec, exec, s[34:35]
	v_pk_add_f32 v[96:97], v[96:97], v[160:161]
	v_pk_add_f32 v[94:95], v[94:95], v[158:159]
	v_pk_add_f32 v[100:101], v[92:93], v[156:157]
	v_pk_add_f32 v[92:93], v[90:91], v[154:155]
	v_mul_f32_e32 v90, v95, v95
	v_mul_f32_e32 v91, v97, v97
	v_fmac_f32_e32 v90, v94, v94
	v_fmac_f32_e32 v91, v96, v96
	v_add_f32_e32 v90, v90, v91
	v_mul_f32_e32 v91, v93, v93
	v_mul_f32_e32 v102, v101, v101
	v_fmac_f32_e32 v91, v92, v92
	v_fmac_f32_e32 v102, v100, v100
	v_add_f32_e32 v91, v91, v102
	v_pk_add_f32 v[88:89], v[88:89], v[152:153]
	v_pk_add_f32 v[86:87], v[86:87], v[150:151]
	v_add_f32_e32 v102, v90, v91
	v_cvt_pk_bf16_f32 v91, v96, v97
	v_pk_add_f32 v[96:97], v[82:83], v[146:147]
	v_mul_f32_e32 v82, v87, v87
	v_mul_f32_e32 v83, v89, v89
	v_cvt_pk_bf16_f32 v90, v94, v95
	v_pk_add_f32 v[94:95], v[84:85], v[148:149]
	v_fmac_f32_e32 v82, v86, v86
	v_fmac_f32_e32 v83, v88, v88
	v_add_f32_e32 v82, v82, v83
	v_mul_f32_e32 v83, v97, v97
	v_mul_f32_e32 v84, v95, v95
	v_fmac_f32_e32 v83, v96, v96
	v_fmac_f32_e32 v84, v94, v94
	v_add_f32_e32 v83, v83, v84
	v_add_f32_e32 v82, v82, v83
	v_add_f32_e32 v82, v102, v82
	ds_bpermute_b32 v83, v216, v82
	s_waitcnt lgkmcnt(1)
	v_lshlrev_b64 v[98:99], 13, v[202:203]
	v_lshl_add_u64 v[98:99], v[194:195], 0, v[98:99]
	v_cvt_pk_bf16_f32 v92, v92, v93
	v_cvt_pk_bf16_f32 v93, v100, v101
	s_waitcnt lgkmcnt(0)
	v_add_f32_e32 v82, v82, v83
	ds_bpermute_b32 v83, v199, v82
	v_cvt_pk_bf16_f32 v84, v86, v87
	v_cvt_pk_bf16_f32 v85, v88, v89
	v_cvt_pk_bf16_f32 v86, v96, v97
	v_cvt_pk_bf16_f32 v87, v94, v95
	global_store_dwordx4 v[98:99], v[90:93], off nt
	global_store_dwordx4 v[98:99], v[84:87], off offset:256 nt
	s_and_saveexec_b64 s[34:35], s[8:9]
	s_cbranch_execz .LBB0_700
	s_waitcnt lgkmcnt(0)
	v_add_f32_e32 v82, v82, v83
	ds_write_b32 v215, v82 offset:128
.LBB0_700:
	s_or_b64 exec, exec, s[34:35]
	v_pk_add_f32 v[80:81], v[80:81], v[144:145]
	v_pk_add_f32 v[78:79], v[78:79], v[142:143]
	v_pk_add_f32 v[84:85], v[76:77], v[140:141]
	v_pk_add_f32 v[76:77], v[74:75], v[138:139]
	v_mul_f32_e32 v74, v79, v79
	v_mul_f32_e32 v75, v81, v81
	v_fmac_f32_e32 v74, v78, v78
	v_fmac_f32_e32 v75, v80, v80
	v_add_f32_e32 v74, v74, v75
	v_mul_f32_e32 v75, v77, v77
	v_mul_f32_e32 v86, v85, v85
	v_fmac_f32_e32 v75, v76, v76
	v_fmac_f32_e32 v86, v84, v84
	v_add_f32_e32 v75, v75, v86
	v_pk_add_f32 v[72:73], v[72:73], v[136:137]
	v_pk_add_f32 v[70:71], v[70:71], v[134:135]
	v_add_f32_e32 v86, v74, v75
	v_cvt_pk_bf16_f32 v75, v80, v81
	v_pk_add_f32 v[80:81], v[66:67], v[130:131]
	v_mul_f32_e32 v66, v71, v71
	v_mul_f32_e32 v67, v73, v73
	v_cvt_pk_bf16_f32 v74, v78, v79
	v_pk_add_f32 v[78:79], v[68:69], v[132:133]
	v_fmac_f32_e32 v66, v70, v70
	v_fmac_f32_e32 v67, v72, v72
	v_add_f32_e32 v66, v66, v67
	v_mul_f32_e32 v67, v81, v81
	v_mul_f32_e32 v68, v79, v79
	v_fmac_f32_e32 v67, v80, v80
	v_fmac_f32_e32 v68, v78, v78
	v_add_f32_e32 v67, v67, v68
	v_add_f32_e32 v66, v66, v67
	v_add_f32_e32 v66, v86, v66
	ds_bpermute_b32 v67, v216, v66
	s_waitcnt lgkmcnt(1)
	v_lshlrev_b64 v[82:83], 13, v[200:201]
	v_lshl_add_u64 v[82:83], v[194:195], 0, v[82:83]
	v_cvt_pk_bf16_f32 v76, v76, v77
	v_cvt_pk_bf16_f32 v77, v84, v85
	s_waitcnt lgkmcnt(0)
	v_add_f32_e32 v66, v66, v67
	ds_bpermute_b32 v67, v199, v66
	v_cvt_pk_bf16_f32 v68, v70, v71
	v_cvt_pk_bf16_f32 v69, v72, v73
	v_cvt_pk_bf16_f32 v70, v80, v81
	v_cvt_pk_bf16_f32 v71, v78, v79
	global_store_dwordx4 v[82:83], v[74:77], off nt
	global_store_dwordx4 v[82:83], v[68:71], off offset:256 nt
	s_and_saveexec_b64 s[34:35], s[8:9]
	s_cbranch_execz .LBB0_702
	s_waitcnt lgkmcnt(0)
	v_add_f32_e32 v66, v66, v67
	ds_write_b32 v215, v66 offset:192
.LBB0_702:
	s_or_b64 exec, exec, s[34:35]
	v_add_u32_e32 v136, 0x80, v198
	v_ashrrev_i32_e32 v137, 31, v136
	s_waitcnt lgkmcnt(0)
	v_lshlrev_b64 v[66:67], 14, v[136:137]
	v_lshl_add_u64 v[66:67], v[196:197], 0, v[66:67]
	global_load_dwordx4 v[120:123], v[66:67], off
	global_load_dwordx4 v[124:127], v[66:67], off offset:16
	global_load_dwordx4 v[128:131], v[66:67], off offset:512
	global_load_dwordx4 v[132:135], v[66:67], off offset:528
	v_add_u32_e32 v118, 0x90, v198
	v_add_u32_e32 v116, 0xa0, v198
	v_add_u32_e32 v114, 0xb0, v198
	v_ashrrev_i32_e32 v119, 31, v118
	v_ashrrev_i32_e32 v117, 31, v116
	v_ashrrev_i32_e32 v115, 31, v114
	v_lshlrev_b64 v[66:67], 14, v[118:119]
	v_lshlrev_b64 v[68:69], 14, v[116:117]
	v_lshlrev_b64 v[70:71], 14, v[114:115]
	v_lshl_add_u64 v[66:67], v[196:197], 0, v[66:67]
	v_lshl_add_u64 v[68:69], v[196:197], 0, v[68:69]
	v_lshl_add_u64 v[70:71], v[196:197], 0, v[70:71]
	global_load_dwordx4 v[106:109], v[66:67], off offset:16
	global_load_dwordx4 v[110:113], v[66:67], off
	global_load_dwordx4 v[98:101], v[66:67], off offset:528
	global_load_dwordx4 v[102:105], v[66:67], off offset:512
	global_load_dwordx4 v[90:93], v[68:69], off offset:16
	global_load_dwordx4 v[94:97], v[68:69], off
	global_load_dwordx4 v[82:85], v[68:69], off offset:528
	global_load_dwordx4 v[86:89], v[68:69], off offset:512
	global_load_dwordx4 v[74:77], v[70:71], off offset:16
	global_load_dwordx4 v[78:81], v[70:71], off
	s_nop 0
	global_load_dwordx4 v[66:69], v[70:71], off offset:528
	s_nop 0
	global_load_dwordx4 v[70:73], v[70:71], off offset:512
	v_lshlrev_b64 v[136:137], 13, v[136:137]
	v_lshl_add_u64 v[136:137], v[194:195], 0, v[136:137]
	s_waitcnt vmcnt(15)
	v_pk_add_f32 v[64:65], v[64:65], v[122:123]
	v_pk_add_f32 v[62:63], v[62:63], v[120:121]
	s_waitcnt vmcnt(14)
	v_pk_add_f32 v[60:61], v[60:61], v[126:127]
	v_pk_add_f32 v[58:59], v[58:59], v[124:125]
	s_waitcnt vmcnt(13)
	v_pk_add_f32 v[56:57], v[56:57], v[130:131]
	v_pk_add_f32 v[54:55], v[54:55], v[128:129]
	s_waitcnt vmcnt(12)
	v_pk_add_f32 v[120:121], v[52:53], v[134:135]
	v_pk_add_f32 v[122:123], v[50:51], v[132:133]
	v_mul_f32_e32 v52, v63, v63
	v_mul_f32_e32 v53, v65, v65
	v_mul_f32_e32 v124, v59, v59
	v_mul_f32_e32 v125, v61, v61
	v_cvt_pk_bf16_f32 v50, v62, v63
	v_cvt_pk_bf16_f32 v51, v64, v65
	v_mul_f32_e32 v63, v55, v55
	v_mul_f32_e32 v65, v57, v57
	v_mul_f32_e32 v126, v123, v123
	v_mul_f32_e32 v127, v121, v121
	v_fmac_f32_e32 v52, v62, v62
	v_fmac_f32_e32 v53, v64, v64
	v_fmac_f32_e32 v124, v58, v58
	v_fmac_f32_e32 v125, v60, v60
	v_fmac_f32_e32 v63, v54, v54
	v_fmac_f32_e32 v65, v56, v56
	v_fmac_f32_e32 v126, v122, v122
	v_fmac_f32_e32 v127, v120, v120
	v_add_f32_e32 v52, v52, v53
	v_add_f32_e32 v53, v124, v125
	v_add_f32_e32 v62, v63, v65
	v_add_f32_e32 v63, v126, v127
	v_add_f32_e32 v52, v52, v53
	v_add_f32_e32 v53, v62, v63
	v_add_f32_e32 v62, v52, v53
	ds_bpermute_b32 v63, v216, v62
	v_cvt_pk_bf16_f32 v52, v58, v59
	v_cvt_pk_bf16_f32 v53, v60, v61
	global_store_dwordx4 v[136:137], v[50:53], off nt
	s_waitcnt lgkmcnt(0)
	s_nop 0
	v_add_f32_e32 v50, v62, v63
	ds_bpermute_b32 v51, v199, v50
	v_cvt_pk_bf16_f32 v52, v54, v55
	v_cvt_pk_bf16_f32 v53, v56, v57
	v_cvt_pk_bf16_f32 v54, v122, v123
	v_cvt_pk_bf16_f32 v55, v120, v121
	global_store_dwordx4 v[136:137], v[52:55], off offset:256 nt
	s_and_saveexec_b64 s[34:35], s[8:9]
	s_cbranch_execz .LBB0_704
; #define PG8_GAS __attribute__((address_space(1)))
; __device__ __forceinline__ unsigned cvt_pk_bf16(float lo, float hi) { const f32x2c v = {lo, hi}; return __builtin_bit_cast(unsigned, __builtin_convertvector(v, bf16x2c)); }
;     __device__ __forceinline__ void run(const f32x4 (&acc)[2][2][4][2], const Unit& un, int wr, int wc, int fr, int fq, PG8_LAS unsigned char* xl) const {
;     ...
;             for (int m = 0; m < 4; ++m) { float s = 0.f;
; #pragma unroll
;                 for (int bj = 0; bj < 2; ++bj) { const f32x4 h0 = bb[m][bj][0] + acc[ai][bj][m][0], h1 = bb[m][bj][1] + acc[ai][bj][m][1];
;                     s += ((h0[0] * h0[0] + h0[1] * h0[1]) + (h0[2] * h0[2] + h0[3] * h0[3])) + ((h1[0] * h1[0] + h1[1] * h1[1]) + (h1[2] * h1[2] + h1[3] * h1[3]));
;                     u32x4 w; w.x = cvt_pk_bf16(h0[0], h0[1]); w.y = cvt_pk_bf16(h0[2], h0[3]); w.z = cvt_pk_bf16(h1[0], h1[1]); w.w = cvt_pk_bf16(h1[2], h1[3]);
;                     *(PG8_GAS u32x4*)(hs + (size_t)(rloc + ai * HALF + m * 16) * 4096 + col0 + bj * HALF) = w; }
;                 s += __shfl_xor(s, 16); s += __shfl_xor(s, 32);
;                 if (fq == 0) X[wc * 256 + rloc + ai * HALF + m * 16] = s; }
	s_waitcnt lgkmcnt(0)
	v_add_f32_e32 v50, v50, v51
	ds_write_b32 v215, v50 offset:512
.LBB0_704:
	s_or_b64 exec, exec, s[34:35]
	s_waitcnt vmcnt(12)
	v_pk_add_f32 v[48:49], v[48:49], v[112:113]
	v_pk_add_f32 v[46:47], v[46:47], v[110:111]
	v_pk_add_f32 v[52:53], v[44:45], v[108:109]
	v_pk_add_f32 v[44:45], v[42:43], v[106:107]
	v_mul_f32_e32 v42, v47, v47
	v_mul_f32_e32 v43, v49, v49
	v_fmac_f32_e32 v42, v46, v46
	v_fmac_f32_e32 v43, v48, v48
	v_add_f32_e32 v42, v42, v43
	v_mul_f32_e32 v43, v45, v45
	v_mul_f32_e32 v54, v53, v53
	v_fmac_f32_e32 v43, v44, v44
	v_fmac_f32_e32 v54, v52, v52
	v_add_f32_e32 v43, v43, v54
	s_waitcnt vmcnt(10)
	v_pk_add_f32 v[40:41], v[40:41], v[104:105]
	v_pk_add_f32 v[38:39], v[38:39], v[102:103]
	v_add_f32_e32 v54, v42, v43
	v_cvt_pk_bf16_f32 v43, v48, v49
	v_pk_add_f32 v[48:49], v[34:35], v[98:99]
	v_mul_f32_e32 v34, v39, v39
	v_mul_f32_e32 v35, v41, v41
	v_cvt_pk_bf16_f32 v42, v46, v47
	v_pk_add_f32 v[46:47], v[36:37], v[100:101]
	v_fmac_f32_e32 v34, v38, v38
	v_fmac_f32_e32 v35, v40, v40
	v_add_f32_e32 v34, v34, v35
	v_mul_f32_e32 v35, v49, v49
	v_mul_f32_e32 v36, v47, v47
	v_fmac_f32_e32 v35, v48, v48
	v_fmac_f32_e32 v36, v46, v46
	v_add_f32_e32 v35, v35, v36
	v_add_f32_e32 v34, v34, v35
	v_add_f32_e32 v34, v54, v34
	ds_bpermute_b32 v35, v216, v34
	s_waitcnt lgkmcnt(1)
	v_lshlrev_b64 v[50:51], 13, v[118:119]
	v_lshl_add_u64 v[50:51], v[194:195], 0, v[50:51]
	v_cvt_pk_bf16_f32 v44, v44, v45
	v_cvt_pk_bf16_f32 v45, v52, v53
	s_waitcnt lgkmcnt(0)
	v_add_f32_e32 v34, v34, v35
	ds_bpermute_b32 v35, v199, v34
	v_cvt_pk_bf16_f32 v36, v38, v39
	v_cvt_pk_bf16_f32 v37, v40, v41
	v_cvt_pk_bf16_f32 v38, v48, v49
	v_cvt_pk_bf16_f32 v39, v46, v47
	global_store_dwordx4 v[50:51], v[42:45], off nt
	global_store_dwordx4 v[50:51], v[36:39], off offset:256 nt
	s_and_saveexec_b64 s[34:35], s[8:9]
	s_cbranch_execz .LBB0_706
	s_waitcnt lgkmcnt(0)
	v_add_f32_e32 v34, v34, v35
	ds_write_b32 v215, v34 offset:576
.LBB0_706:
	s_or_b64 exec, exec, s[34:35]
	s_waitcnt vmcnt(10)
	v_pk_add_f32 v[32:33], v[32:33], v[96:97]
	v_pk_add_f32 v[30:31], v[30:31], v[94:95]
	v_pk_add_f32 v[36:37], v[28:29], v[92:93]
	v_pk_add_f32 v[28:29], v[26:27], v[90:91]
	v_mul_f32_e32 v26, v31, v31
	v_mul_f32_e32 v27, v33, v33
	v_fmac_f32_e32 v26, v30, v30
	v_fmac_f32_e32 v27, v32, v32
	v_add_f32_e32 v26, v26, v27
	v_mul_f32_e32 v27, v29, v29
	v_mul_f32_e32 v38, v37, v37
	v_fmac_f32_e32 v27, v28, v28
	v_fmac_f32_e32 v38, v36, v36
	v_add_f32_e32 v27, v27, v38
	s_waitcnt vmcnt(8)
	v_pk_add_f32 v[24:25], v[24:25], v[88:89]
	v_pk_add_f32 v[22:23], v[22:23], v[86:87]
	v_add_f32_e32 v38, v26, v27
	v_cvt_pk_bf16_f32 v27, v32, v33
	v_pk_add_f32 v[32:33], v[18:19], v[82:83]
	v_mul_f32_e32 v18, v23, v23
	v_mul_f32_e32 v19, v25, v25
	v_cvt_pk_bf16_f32 v26, v30, v31
	v_pk_add_f32 v[30:31], v[20:21], v[84:85]
	v_fmac_f32_e32 v18, v22, v22
	v_fmac_f32_e32 v19, v24, v24
	v_add_f32_e32 v18, v18, v19
	v_mul_f32_e32 v19, v33, v33
	v_mul_f32_e32 v20, v31, v31
	v_fmac_f32_e32 v19, v32, v32
	v_fmac_f32_e32 v20, v30, v30
	v_add_f32_e32 v19, v19, v20
	v_add_f32_e32 v18, v18, v19
	v_add_f32_e32 v18, v38, v18
	ds_bpermute_b32 v19, v216, v18
	s_waitcnt lgkmcnt(1)
	v_lshlrev_b64 v[34:35], 13, v[116:117]
	v_lshl_add_u64 v[34:35], v[194:195], 0, v[34:35]
	v_cvt_pk_bf16_f32 v28, v28, v29
	v_cvt_pk_bf16_f32 v29, v36, v37
	s_waitcnt lgkmcnt(0)
	v_add_f32_e32 v18, v18, v19
	ds_bpermute_b32 v19, v199, v18
	v_cvt_pk_bf16_f32 v20, v22, v23
	v_cvt_pk_bf16_f32 v21, v24, v25
	v_cvt_pk_bf16_f32 v22, v32, v33
	v_cvt_pk_bf16_f32 v23, v30, v31
	global_store_dwordx4 v[34:35], v[26:29], off nt
	global_store_dwordx4 v[34:35], v[20:23], off offset:256 nt
	s_and_saveexec_b64 s[34:35], s[8:9]
	s_cbranch_execz .LBB0_708
	s_waitcnt lgkmcnt(0)
	v_add_f32_e32 v18, v18, v19
	ds_write_b32 v215, v18 offset:640
.LBB0_708:
	s_or_b64 exec, exec, s[34:35]
	s_waitcnt vmcnt(8)
	v_pk_add_f32 v[16:17], v[16:17], v[80:81]
	v_pk_add_f32 v[14:15], v[14:15], v[78:79]
	v_pk_add_f32 v[20:21], v[12:13], v[76:77]
	v_pk_add_f32 v[12:13], v[10:11], v[74:75]
	v_mul_f32_e32 v10, v15, v15
	v_mul_f32_e32 v11, v17, v17
	v_fmac_f32_e32 v10, v14, v14
	v_fmac_f32_e32 v11, v16, v16
	v_add_f32_e32 v10, v10, v11
	v_mul_f32_e32 v11, v13, v13
	v_mul_f32_e32 v22, v21, v21
	v_fmac_f32_e32 v11, v12, v12
	v_fmac_f32_e32 v22, v20, v20
	v_add_f32_e32 v11, v11, v22
	s_waitcnt vmcnt(6)
	v_pk_add_f32 v[8:9], v[8:9], v[72:73]
	v_pk_add_f32 v[6:7], v[6:7], v[70:71]
	v_add_f32_e32 v22, v10, v11
	v_cvt_pk_bf16_f32 v11, v16, v17
	v_pk_add_f32 v[16:17], v[2:3], v[66:67]
	v_mul_f32_e32 v2, v7, v7
	v_mul_f32_e32 v3, v9, v9
	v_cvt_pk_bf16_f32 v10, v14, v15
	v_pk_add_f32 v[14:15], v[4:5], v[68:69]
	v_fmac_f32_e32 v2, v6, v6
	v_fmac_f32_e32 v3, v8, v8
	v_add_f32_e32 v2, v2, v3
	v_mul_f32_e32 v3, v17, v17
	v_mul_f32_e32 v4, v15, v15
	v_fmac_f32_e32 v3, v16, v16
	v_fmac_f32_e32 v4, v14, v14
	v_add_f32_e32 v3, v3, v4
	v_add_f32_e32 v2, v2, v3
	v_add_f32_e32 v2, v22, v2
	ds_bpermute_b32 v3, v216, v2
	s_waitcnt lgkmcnt(1)
	v_lshlrev_b64 v[18:19], 13, v[114:115]
	v_lshl_add_u64 v[18:19], v[194:195], 0, v[18:19]
	v_cvt_pk_bf16_f32 v12, v12, v13
	v_cvt_pk_bf16_f32 v13, v20, v21
	s_waitcnt lgkmcnt(0)
	v_add_f32_e32 v2, v2, v3
	ds_bpermute_b32 v3, v199, v2
	v_cvt_pk_bf16_f32 v4, v6, v7
	v_cvt_pk_bf16_f32 v5, v8, v9
	v_cvt_pk_bf16_f32 v6, v16, v17
	v_cvt_pk_bf16_f32 v7, v14, v15
	global_store_dwordx4 v[18:19], v[10:13], off nt
	global_store_dwordx4 v[18:19], v[4:7], off offset:256 nt
	s_and_saveexec_b64 s[34:35], s[8:9]
	s_cbranch_execz .LBB0_710
	s_waitcnt lgkmcnt(0)
	v_add_f32_e32 v2, v2, v3
	ds_write_b32 v215, v2 offset:704

; #define PG8_GAS __attribute__((address_space(1)))
; __device__ __forceinline__ unsigned cvt_pk_bf16(float lo, float hi) { const f32x2c v = {lo, hi}; return __builtin_bit_cast(unsigned, __builtin_convertvector(v, bf16x2c)); }
; __device__ __forceinline__ float fma_s(float a, float b, float c) { float d; asm("v_fma_f32 %0, %1, %2, %3" : "=v"(d) : "v"(a), "v"(b), "v"(c)); return d; }
; #define PG8_ROR1(x) dpp_ror1(x)
; #define PG8_ROR15(x) dpp_ror15(x)
;     __device__ __forceinline__ void run(f32x4 (&acc)[2][2][4][2], const Unit& un, int wr, int wc, int fr, int fq, PG8_LAS unsigned char* xl) const {
;     ...
;                 for (int m = 0; m < 4; ++m) {
;                     float o[4];
; #pragma unroll
;                     for (int e = 0; e < 4; ++e) {
;                         const float g = acc[ai][0][m][n][e], v = acc[ai][1][m][n][e];
;                         const float gpe = m > 0 ? PG8_ROR1(acc[ai][0][m - 1][n][e]) : hpg[e], vpe = m > 0 ? PG8_ROR1(acc[ai][1][m - 1][n][e]) : hpv[e];
;                         const float gne = m < 3 ? PG8_ROR15(acc[ai][0][m + 1][n][e]) : hng[e], vne = m < 3 ? PG8_ROR15(acc[ai][1][m + 1][n][e]) : hnv[e];
;                         const float gpi = PG8_ROR1(g), vpi = PG8_ROR1(v), gni = PG8_ROR15(g), vni = PG8_ROR15(v);
;                         const float gp = e0 ? gpe : gpi, vp = e0 ? vpe : vpi, gn = e15 ? gne : gni, vn = e15 ? vne : vni;
;                         const float cg = fma_s(w2g[e], gn, fma_s(w1g[e], g, fma_s(w0g[e], gp, bg[e]))), cv = fma_s(w2v[e], vn, fma_s(w1v[e], v, fma_s(w0v[e], vp, bv[e])));
;                         o[e] = (cg * cv) * __builtin_amdgcn_rcpf(1.0f + __builtin_amdgcn_exp2f(cg * -1.4426950408889634f));
;                     }
;                     if (n == 0) { keep[m].x = cvt_pk_bf16(o[0], o[1]); keep[m].y = cvt_pk_bf16(o[2], o[3]); }
;                     else { u32x4 w; w.x = keep[m].x; w.y = keep[m].y; w.z = cvt_pk_bf16(o[0], o[1]); w.w = cvt_pk_bf16(o[2], o[3]);
;                         *(PG8_GAS u32x4*)(act + (size_t)(row0 + ai * HALF + m * 16) * dff + j - 4) = w; }
;                 }
.LBB0_802:
	v_mul_f32_e32 v140, 0xbfb8aa3b, v174
	v_mul_f32_e32 v141, 0xbfb8aa3b, v175
	v_exp_f32_e32 v140, v140
	v_exp_f32_e32 v141, v141
	v_pk_mul_f32 v[142:143], v[174:175], v[224:225]
	v_pk_mul_f32 v[152:153], v[170:171], v[176:177]
	v_add_f32_e32 v140, 1.0, v140
	v_add_f32_e32 v141, 1.0, v141
	v_rcp_f32_e32 v140, v140
	v_rcp_f32_e32 v141, v141
	v_pk_mul_f32 v[168:169], v[218:219], v[226:227]
	v_mov_b32_e32 v215, v214
	v_mov_b32_e32 v217, v216
	v_pk_mul_f32 v[140:141], v[142:143], v[140:141]
	v_mul_f32_e32 v142, 0xbfb8aa3b, v170
	v_mul_f32_e32 v143, 0xbfb8aa3b, v171
	v_exp_f32_e32 v142, v142
	v_exp_f32_e32 v143, v143
	v_pk_mul_f32 v[170:171], v[172:173], v[220:221]
	s_lshl_b32 s14, s76, 8
	v_add_f32_e32 v142, 1.0, v142
	v_add_f32_e32 v143, 1.0, v143
	v_rcp_f32_e32 v142, v142
	v_rcp_f32_e32 v143, v143
	s_add_i32 s14, s14, s34
	v_pk_mul_f32 v[142:143], v[152:153], v[142:143]
	v_cvt_pk_bf16_f32 v152, v140, v141
	v_mul_f32_e32 v140, 0xbfb8aa3b, v228
	v_mul_f32_e32 v141, 0xbfb8aa3b, v229
	v_exp_f32_e32 v140, v140
	v_exp_f32_e32 v141, v141
	v_cvt_pk_bf16_f32 v153, v142, v143
	v_pk_mul_f32 v[142:143], v[228:229], v[234:235]
	v_add_f32_e32 v140, 1.0, v140
	v_add_f32_e32 v141, 1.0, v141
	v_rcp_f32_e32 v140, v140
	v_rcp_f32_e32 v141, v141
	s_waitcnt lgkmcnt(1)
	v_pk_mul_f32 v[140:141], v[142:143], v[140:141]
	v_mul_f32_e32 v142, 0xbfb8aa3b, v218
	v_mul_f32_e32 v143, 0xbfb8aa3b, v219
	v_exp_f32_e32 v142, v142
	v_exp_f32_e32 v143, v143
	v_add_f32_e32 v142, 1.0, v142
	v_add_f32_e32 v143, 1.0, v143
	v_rcp_f32_e32 v142, v142
	v_rcp_f32_e32 v143, v143
	s_waitcnt lgkmcnt(0)
	v_pk_mul_f32 v[168:169], v[168:169], v[142:143]
	v_cvt_pk_bf16_f32 v142, v140, v141
	v_mul_f32_e32 v140, 0xbfb8aa3b, v232
	v_mul_f32_e32 v141, 0xbfb8aa3b, v233
	v_exp_f32_e32 v140, v140
	v_exp_f32_e32 v141, v141
	v_cvt_pk_bf16_f32 v143, v168, v169
	v_pk_mul_f32 v[168:169], v[232:233], v[236:237]
	v_add_f32_e32 v140, 1.0, v140
	v_add_f32_e32 v141, 1.0, v141
	v_rcp_f32_e32 v140, v140
	v_rcp_f32_e32 v141, v141
	s_waitcnt lgkmcnt(0)
	v_pk_mul_f32 v[140:141], v[168:169], v[140:141]
	v_mul_f32_e32 v168, 0xbfb8aa3b, v172
	v_mul_f32_e32 v169, 0xbfb8aa3b, v173
	v_exp_f32_e32 v168, v168
	v_exp_f32_e32 v169, v169
	v_cvt_pk_bf16_f32 v140, v140, v141
	v_add_u32_e32 v172, s14, v210
	v_add_f32_e32 v168, 1.0, v168
	v_add_f32_e32 v169, 1.0, v169
	v_rcp_f32_e32 v168, v168
	v_rcp_f32_e32 v169, v169
	s_waitcnt lgkmcnt(0)
	v_pk_mul_f32 v[168:169], v[170:171], v[168:169]
	v_cvt_pk_bf16_f32 v141, v168, v169
	v_mul_f32_e32 v168, 0xbfb8aa3b, v222
	v_mul_f32_e32 v169, 0xbfb8aa3b, v223
	v_exp_f32_e32 v168, v168
	v_exp_f32_e32 v169, v169
	v_pk_mul_f32 v[170:171], v[222:223], v[230:231]
	v_add_f32_e32 v168, 1.0, v168
	v_add_f32_e32 v169, 1.0, v169
	v_rcp_f32_e32 v168, v168
	v_rcp_f32_e32 v169, v169
	v_fma_f32 v179, v106, v90, v118
	v_pk_mul_f32 v[168:169], v[170:171], v[168:169]
	v_mul_f32_e32 v170, 0xbfb8aa3b, v138
	v_mul_f32_e32 v171, 0xbfb8aa3b, v139
	v_exp_f32_e32 v170, v170
	v_exp_f32_e32 v171, v171
	v_pk_mul_f32 v[138:139], v[138:139], v[154:155]
	v_add_f32_e32 v170, 1.0, v170
	v_add_f32_e32 v171, 1.0, v171
	v_rcp_f32_e32 v170, v170
	v_rcp_f32_e32 v171, v171
	v_fmac_f32_dpp v179, v90, v98 row_shr:1 row_mask:0xf bank_mask:0xf
	v_pk_mul_f32 v[154:155], v[138:139], v[170:171]
	v_cvt_pk_bf16_f32 v139, v154, v155
	v_mov_b32_e32 v154, v214
	v_mov_b32_e32 v155, v214
	v_cvt_pk_bf16_f32 v138, v168, v169
	v_pk_mul_f32 v[168:169], v[86:87], v[214:215]
	v_pk_mul_f32 v[86:87], v[80:81], v[154:155]
	v_pk_mul_f32 v[80:81], v[82:83], v[216:217]
	v_pk_mul_f32 v[82:83], v[74:75], v[216:217]
	v_pk_mul_f32 v[88:89], v[88:89], v[154:155]
	v_mov_b32_e32 v154, v216
	v_mov_b32_e32 v155, v216
	v_pk_mul_f32 v[170:171], v[78:79], v[214:215]
	v_pk_mul_f32 v[78:79], v[84:85], v[154:155]
	v_fmac_f32_dpp v179, v148, v98 row_shl:15 row_mask:0xf bank_mask:0xf
	v_pk_fma_f32 v[84:85], v[114:115], v[94:95], v[126:127]
	v_pk_mul_f32 v[76:77], v[76:77], v[154:155]
	v_fmac_f32_dpp v179, v90, v102 row_shl:1 row_mask:0xf bank_mask:0xf
	v_fmac_f32_dpp v84, v94, v110 row_shr:1 row_mask:0xf bank_mask:0xf
	v_fmac_f32_dpp v85, v95, v111 row_shr:1 row_mask:0xf bank_mask:0xf
	v_fmac_f32_dpp v179, v168, v102 row_shr:15 row_mask:0xf bank_mask:0xf
	v_mov_b32_e32 v74, v179
	v_fmac_f32_dpp v84, v144, v110 row_shl:15 row_mask:0xf bank_mask:0xf
	v_fmac_f32_dpp v85, v145, v111 row_shl:15 row_mask:0xf bank_mask:0xf
	v_mul_f32_e32 v75, 0xbfb8aa3b, v74
	v_fmac_f32_dpp v84, v94, v122 row_shl:1 row_mask:0xf bank_mask:0xf
	v_fmac_f32_dpp v85, v95, v123 row_shl:1 row_mask:0xf bank_mask:0xf
	v_exp_f32_e32 v75, v75
	v_fmac_f32_dpp v84, v170, v122 row_shr:15 row_mask:0xf bank_mask:0xf
	v_fmac_f32_dpp v85, v171, v123 row_shr:15 row_mask:0xf bank_mask:0xf
	v_add_f32_e32 v75, 1.0, v75
	v_rcp_f32_e32 v144, v75
	v_fma_f32 v75, v107, v91, v119
	v_fma_f32 v181, v108, v92, v120
	v_pk_fma_f32 v[248:249], v[116:117], v[96:97], v[128:129]
	v_fmac_f32_dpp v75, v91, v99 row_shr:1 row_mask:0xf bank_mask:0xf
	v_fmac_f32_dpp v181, v92, v100 row_shr:1 row_mask:0xf bank_mask:0xf
	v_fmac_f32_dpp v248, v96, v112 row_shr:1 row_mask:0xf bank_mask:0xf
	v_fmac_f32_dpp v75, v149, v99 row_shl:15 row_mask:0xf bank_mask:0xf
	v_fmac_f32_dpp v181, v150, v100 row_shl:15 row_mask:0xf bank_mask:0xf
	v_fmac_f32_dpp v249, v97, v113 row_shr:1 row_mask:0xf bank_mask:0xf
	v_fmac_f32_dpp v75, v91, v103 row_shl:1 row_mask:0xf bank_mask:0xf
	v_fmac_f32_dpp v181, v92, v104 row_shl:1 row_mask:0xf bank_mask:0xf
	v_fmac_f32_dpp v248, v146, v112 row_shl:15 row_mask:0xf bank_mask:0xf
	v_fmac_f32_dpp v75, v169, v103 row_shr:15 row_mask:0xf bank_mask:0xf
	v_mul_f32_e32 v145, 0xbfb8aa3b, v75
	v_exp_f32_e32 v145, v145
; #define PG8_GAS __attribute__((address_space(1)))
; __device__ __forceinline__ unsigned cvt_pk_bf16(float lo, float hi) { const f32x2c v = {lo, hi}; return __builtin_bit_cast(unsigned, __builtin_convertvector(v, bf16x2c)); }
; __device__ __forceinline__ float fma_s(float a, float b, float c) { float d; asm("v_fma_f32 %0, %1, %2, %3" : "=v"(d) : "v"(a), "v"(b), "v"(c)); return d; }
; #define PG8_ROR1(x) dpp_ror1(x)
; #define PG8_ROR15(x) dpp_ror15(x)
;     __device__ __forceinline__ void run(f32x4 (&acc)[2][2][4][2], const Unit& un, int wr, int wc, int fr, int fq, PG8_LAS unsigned char* xl) const {
;     ...
;                 for (int m = 0; m < 4; ++m) {
;                     float o[4];
; #pragma unroll
;                     for (int e = 0; e < 4; ++e) {
;                         const float g = acc[ai][0][m][n][e], v = acc[ai][1][m][n][e];
;                         const float gpe = m > 0 ? PG8_ROR1(acc[ai][0][m - 1][n][e]) : hpg[e], vpe = m > 0 ? PG8_ROR1(acc[ai][1][m - 1][n][e]) : hpv[e];
;                         const float gne = m < 3 ? PG8_ROR15(acc[ai][0][m + 1][n][e]) : hng[e], vne = m < 3 ? PG8_ROR15(acc[ai][1][m + 1][n][e]) : hnv[e];
;                         const float gpi = PG8_ROR1(g), vpi = PG8_ROR1(v), gni = PG8_ROR15(g), vni = PG8_ROR15(v);
;                         const float gp = e0 ? gpe : gpi, vp = e0 ? vpe : vpi, gn = e15 ? gne : gni, vn = e15 ? vne : vni;
;                         const float cg = fma_s(w2g[e], gn, fma_s(w1g[e], g, fma_s(w0g[e], gp, bg[e]))), cv = fma_s(w2v[e], vn, fma_s(w1v[e], v, fma_s(w0v[e], vp, bv[e])));
;                         o[e] = (cg * cv) * __builtin_amdgcn_rcpf(1.0f + __builtin_amdgcn_exp2f(cg * -1.4426950408889634f));
;                     }
;                     if (n == 0) { keep[m].x = cvt_pk_bf16(o[0], o[1]); keep[m].y = cvt_pk_bf16(o[2], o[3]); }
;                     else { u32x4 w; w.x = keep[m].x; w.y = keep[m].y; w.z = cvt_pk_bf16(o[0], o[1]); w.w = cvt_pk_bf16(o[2], o[3]);
;                         *(PG8_GAS u32x4*)(act + (size_t)(row0 + ai * HALF + m * 16) * dff + j - 4) = w; }
;                 }
	v_pk_mul_f32 v[74:75], v[74:75], v[84:85]
	v_add_f32_e32 v145, 1.0, v145
	v_rcp_f32_e32 v145, v145
	v_fmac_f32_dpp v181, v88, v104 row_shr:15 row_mask:0xf bank_mask:0xf
	v_pk_mul_f32 v[74:75], v[74:75], v[144:145]
	v_mov_b32_e32 v84, v181
	v_fmac_f32_dpp v249, v147, v113 row_shl:15 row_mask:0xf bank_mask:0xf
	v_fmac_f32_dpp v248, v96, v124 row_shl:1 row_mask:0xf bank_mask:0xf
	v_mul_f32_e32 v85, 0xbfb8aa3b, v84
	v_fmac_f32_dpp v249, v97, v125 row_shl:1 row_mask:0xf bank_mask:0xf
	v_fmac_f32_dpp v248, v86, v124 row_shr:15 row_mask:0xf bank_mask:0xf
	v_exp_f32_e32 v85, v85
	v_fmac_f32_dpp v249, v87, v125 row_shr:15 row_mask:0xf bank_mask:0xf
	v_mov_b64_e32 v[144:145], v[248:249]
	v_add_f32_e32 v85, 1.0, v85
	v_rcp_f32_e32 v146, v85
	v_fma_f32 v85, v109, v93, v121
	v_cvt_pk_bf16_f32 v154, v74, v75
	v_mov_b64_e32 v[74:75], s[24:25]
	v_fmac_f32_dpp v85, v93, v101 row_shr:1 row_mask:0xf bank_mask:0xf
	v_fma_f32 v183, v106, v168, v118
	v_pk_fma_f32 v[250:251], v[114:115], v[170:171], v[126:127]
	v_fma_f32 v185, v107, v169, v119
	v_fmac_f32_dpp v85, v151, v101 row_shl:15 row_mask:0xf bank_mask:0xf
	v_fmac_f32_dpp v183, v168, v98 row_shr:1 row_mask:0xf bank_mask:0xf
	v_fmac_f32_dpp v250, v170, v110 row_shr:1 row_mask:0xf bank_mask:0xf
	v_fmac_f32_dpp v85, v93, v105 row_shl:1 row_mask:0xf bank_mask:0xf
	v_fmac_f32_dpp v183, v90, v98 row_shl:15 row_mask:0xf bank_mask:0xf
	v_fmac_f32_dpp v251, v171, v111 row_shr:1 row_mask:0xf bank_mask:0xf
	v_fmac_f32_dpp v85, v89, v105 row_shr:15 row_mask:0xf bank_mask:0xf
	v_mul_f32_e32 v147, 0xbfb8aa3b, v85
	v_exp_f32_e32 v147, v147
	v_pk_mul_f32 v[84:85], v[84:85], v[144:145]
	v_add_f32_e32 v147, 1.0, v147
	v_rcp_f32_e32 v147, v147
	v_fmac_f32_dpp v183, v168, v102 row_shl:1 row_mask:0xf bank_mask:0xf
	v_pk_mul_f32 v[84:85], v[84:85], v[146:147]
	v_cvt_pk_bf16_f32 v155, v84, v85
	v_mad_i64_i32 v[84:85], s[14:15], v172, s5, v[74:75]
	v_lshlrev_b64 v[146:147], 1, v[212:213]
	v_lshl_add_u64 v[84:85], v[84:85], 0, v[146:147]
	global_store_dwordx4 v[84:85], v[152:155], off nt
	v_fmac_f32_dpp v183, v80, v102 row_shr:15 row_mask:0xf bank_mask:0xf
	v_mov_b32_e32 v84, v183
	v_fmac_f32_dpp v250, v94, v110 row_shl:15 row_mask:0xf bank_mask:0xf
	v_fmac_f32_dpp v251, v95, v111 row_shl:15 row_mask:0xf bank_mask:0xf
	v_mul_f32_e32 v85, 0xbfb8aa3b, v84
	v_fmac_f32_dpp v250, v170, v122 row_shl:1 row_mask:0xf bank_mask:0xf
	v_fmac_f32_dpp v251, v171, v123 row_shl:1 row_mask:0xf bank_mask:0xf
	v_exp_f32_e32 v85, v85
	v_fmac_f32_dpp v250, v82, v122 row_shr:15 row_mask:0xf bank_mask:0xf
	v_fmac_f32_dpp v251, v83, v123 row_shr:15 row_mask:0xf bank_mask:0xf
	v_add_f32_e32 v85, 1.0, v85
	v_rcp_f32_e32 v94, v85
	v_fmac_f32_dpp v185, v169, v99 row_shr:1 row_mask:0xf bank_mask:0xf
	v_fma_f32 v255, v108, v88, v120
	v_fma_f32 v179, v108, v78, v120
	v_fma_f32 v181, v108, v68, v120
	v_fmac_f32_dpp v185, v91, v99 row_shl:15 row_mask:0xf bank_mask:0xf
	v_mov_b64_e32 v[90:91], v[250:251]
	v_fmac_f32_dpp v255, v88, v100 row_shr:1 row_mask:0xf bank_mask:0xf
	v_fmac_f32_dpp v185, v169, v103 row_shl:1 row_mask:0xf bank_mask:0xf
	v_pk_fma_f32 v[252:253], v[116:117], v[86:87], v[128:129]
	v_pk_fma_f32 v[248:249], v[116:117], v[76:77], v[128:129]
	v_fma_f32 v183, v116, v72, v128
	v_fma_f32 v250, v117, v73, v129
	v_fmac_f32_dpp v185, v81, v103 row_shr:15 row_mask:0xf bank_mask:0xf
	v_mov_b32_e32 v85, v185
	v_mul_f32_e32 v95, 0xbfb8aa3b, v85
	v_exp_f32_e32 v95, v95
	v_pk_mul_f32 v[84:85], v[84:85], v[90:91]
	v_add_f32_e32 v95, 1.0, v95
	v_rcp_f32_e32 v95, v95
	v_fmac_f32_dpp v255, v92, v100 row_shl:15 row_mask:0xf bank_mask:0xf
	v_pk_mul_f32 v[84:85], v[84:85], v[94:95]
	v_fmac_f32_dpp v252, v86, v112 row_shr:1 row_mask:0xf bank_mask:0xf
	v_fmac_f32_dpp v255, v88, v104 row_shl:1 row_mask:0xf bank_mask:0xf
	v_fmac_f32_dpp v253, v87, v113 row_shr:1 row_mask:0xf bank_mask:0xf
	v_fmac_f32_dpp v252, v96, v112 row_shl:15 row_mask:0xf bank_mask:0xf
	v_fmac_f32_dpp v255, v78, v104 row_shr:15 row_mask:0xf bank_mask:0xf
	v_fmac_f32_dpp v253, v97, v113 row_shl:15 row_mask:0xf bank_mask:0xf
	v_fmac_f32_dpp v252, v86, v124 row_shl:1 row_mask:0xf bank_mask:0xf
	v_cvt_pk_bf16_f32 v144, v84, v85
	v_fmac_f32_dpp v253, v87, v125 row_shl:1 row_mask:0xf bank_mask:0xf
	v_fmac_f32_dpp v252, v76, v124 row_shr:15 row_mask:0xf bank_mask:0xf
	v_add_u32_e32 v84, 16, v172
	v_fmac_f32_dpp v253, v77, v125 row_shr:15 row_mask:0xf bank_mask:0xf
	v_mad_i64_i32 v[84:85], s[14:15], v84, s5, v[74:75]
	v_lshl_add_u64 v[84:85], v[84:85], 0, v[146:147]
	v_fmac_f32_dpp v179, v78, v100 row_shr:1 row_mask:0xf bank_mask:0xf
	v_fmac_f32_dpp v248, v76, v112 row_shr:1 row_mask:0xf bank_mask:0xf
	v_fmac_f32_dpp v249, v77, v113 row_shr:1 row_mask:0xf bank_mask:0xf
	v_fmac_f32_dpp v179, v88, v100 row_shl:15 row_mask:0xf bank_mask:0xf
	v_mov_b32_e32 v88, v255
	v_mul_f32_e32 v90, 0xbfb8aa3b, v88
	v_exp_f32_e32 v90, v90
	v_fmac_f32_dpp v179, v78, v104 row_shl:1 row_mask:0xf bank_mask:0xf
	v_add_f32_e32 v90, 1.0, v90
	v_rcp_f32_e32 v90, v90
	v_fmac_f32_dpp v179, v68, v104 row_shr:15 row_mask:0xf bank_mask:0xf
	v_fmac_f32_dpp v248, v86, v112 row_shl:15 row_mask:0xf bank_mask:0xf
	v_fmac_f32_dpp v249, v87, v113 row_shl:15 row_mask:0xf bank_mask:0xf
	v_mov_b64_e32 v[86:87], v[252:253]
	v_fma_f32 v251, v109, v89, v121
	v_fma_f32 v185, v109, v79, v121
	v_fma_f32 v255, v109, v69, v121
	v_fmac_f32_dpp v251, v89, v101 row_shr:1 row_mask:0xf bank_mask:0xf
	v_fmac_f32_dpp v248, v76, v124 row_shl:1 row_mask:0xf bank_mask:0xf
	v_fmac_f32_dpp v249, v77, v125 row_shl:1 row_mask:0xf bank_mask:0xf
	v_fmac_f32_dpp v251, v93, v101 row_shl:15 row_mask:0xf bank_mask:0xf
	v_fmac_f32_dpp v248, v72, v124 row_shr:15 row_mask:0xf bank_mask:0xf
; #define PG8_GAS __attribute__((address_space(1)))
; __device__ __forceinline__ unsigned cvt_pk_bf16(float lo, float hi) { const f32x2c v = {lo, hi}; return __builtin_bit_cast(unsigned, __builtin_convertvector(v, bf16x2c)); }
; __device__ __forceinline__ float fma_s(float a, float b, float c) { float d; asm("v_fma_f32 %0, %1, %2, %3" : "=v"(d) : "v"(a), "v"(b), "v"(c)); return d; }
; #define PG8_ROR1(x) dpp_ror1(x)
; #define PG8_ROR15(x) dpp_ror15(x)
;     __device__ __forceinline__ void run(f32x4 (&acc)[2][2][4][2], const Unit& un, int wr, int wc, int fr, int fq, PG8_LAS unsigned char* xl) const {
;     ...
;                 for (int m = 0; m < 4; ++m) {
;                     float o[4];
; #pragma unroll
;                     for (int e = 0; e < 4; ++e) {
;                         const float g = acc[ai][0][m][n][e], v = acc[ai][1][m][n][e];
;                         const float gpe = m > 0 ? PG8_ROR1(acc[ai][0][m - 1][n][e]) : hpg[e], vpe = m > 0 ? PG8_ROR1(acc[ai][1][m - 1][n][e]) : hpv[e];
;                         const float gne = m < 3 ? PG8_ROR15(acc[ai][0][m + 1][n][e]) : hng[e], vne = m < 3 ? PG8_ROR15(acc[ai][1][m + 1][n][e]) : hnv[e];
;                         const float gpi = PG8_ROR1(g), vpi = PG8_ROR1(v), gni = PG8_ROR15(g), vni = PG8_ROR15(v);
;                         const float gp = e0 ? gpe : gpi, vp = e0 ? vpe : vpi, gn = e15 ? gne : gni, vn = e15 ? vne : vni;
;                         const float cg = fma_s(w2g[e], gn, fma_s(w1g[e], g, fma_s(w0g[e], gp, bg[e]))), cv = fma_s(w2v[e], vn, fma_s(w1v[e], v, fma_s(w0v[e], vp, bv[e])));
;                         o[e] = (cg * cv) * __builtin_amdgcn_rcpf(1.0f + __builtin_amdgcn_exp2f(cg * -1.4426950408889634f));
;                     }
;                     if (n == 0) { keep[m].x = cvt_pk_bf16(o[0], o[1]); keep[m].y = cvt_pk_bf16(o[2], o[3]); }
;                     else { u32x4 w; w.x = keep[m].x; w.y = keep[m].y; w.z = cvt_pk_bf16(o[0], o[1]); w.w = cvt_pk_bf16(o[2], o[3]);
;                         *(PG8_GAS u32x4*)(act + (size_t)(row0 + ai * HALF + m * 16) * dff + j - 4) = w; }
;                 }
	v_fmac_f32_dpp v249, v73, v125 row_shr:15 row_mask:0xf bank_mask:0xf
	v_fmac_f32_dpp v251, v89, v105 row_shl:1 row_mask:0xf bank_mask:0xf
	v_fmac_f32_dpp v185, v79, v101 row_shr:1 row_mask:0xf bank_mask:0xf
	v_fmac_f32_dpp v181, v68, v100 row_shr:1 row_mask:0xf bank_mask:0xf
	v_fmac_f32_dpp v251, v79, v105 row_shr:15 row_mask:0xf bank_mask:0xf
	v_fmac_f32_dpp v185, v89, v101 row_shl:15 row_mask:0xf bank_mask:0xf
	v_mov_b32_e32 v89, v251
	v_mul_f32_e32 v91, 0xbfb8aa3b, v89
	v_exp_f32_e32 v91, v91
	v_pk_mul_f32 v[86:87], v[88:89], v[86:87]
	v_add_f32_e32 v91, 1.0, v91
	v_rcp_f32_e32 v91, v91
	v_fmac_f32_dpp v185, v79, v105 row_shl:1 row_mask:0xf bank_mask:0xf
	v_pk_mul_f32 v[86:87], v[86:87], v[90:91]
	v_cvt_pk_bf16_f32 v145, v86, v87
	global_store_dwordx4 v[84:85], v[142:145], off nt
	v_fmac_f32_dpp v185, v69, v105 row_shr:15 row_mask:0xf bank_mask:0xf
	v_fmac_f32_dpp v181, v78, v100 row_shl:15 row_mask:0xf bank_mask:0xf
	v_mov_b32_e32 v78, v179
	v_fmac_f32_dpp v183, v72, v112 row_shr:1 row_mask:0xf bank_mask:0xf
	v_fmac_f32_dpp v181, v68, v104 row_shl:1 row_mask:0xf bank_mask:0xf
	v_fmac_f32_dpp v255, v69, v101 row_shr:1 row_mask:0xf bank_mask:0xf
	v_fmac_f32_dpp v183, v76, v112 row_shl:15 row_mask:0xf bank_mask:0xf
	v_fmac_f32_dpp v181, v136, v104 row_shr:15 row_mask:0xf bank_mask:0xf
	v_mov_b32_e32 v68, v181
	v_fma_f32 v251, v106, v80, v118
	v_fma_f32 v179, v106, v66, v118
	v_fmac_f32_dpp v183, v72, v124 row_shl:1 row_mask:0xf bank_mask:0xf
	v_fmac_f32_dpp v251, v80, v98 row_shr:1 row_mask:0xf bank_mask:0xf
	v_fmac_f32_dpp v179, v66, v98 row_shr:1 row_mask:0xf bank_mask:0xf
	v_fmac_f32_dpp v183, v132, v124 row_shr:15 row_mask:0xf bank_mask:0xf
	v_fmac_f32_dpp v251, v168, v98 row_shl:15 row_mask:0xf bank_mask:0xf
	v_fmac_f32_dpp v179, v80, v98 row_shl:15 row_mask:0xf bank_mask:0xf
	v_fmac_f32_dpp v255, v79, v101 row_shl:15 row_mask:0xf bank_mask:0xf
	v_fmac_f32_dpp v251, v80, v102 row_shl:1 row_mask:0xf bank_mask:0xf
	v_mov_b32_e32 v79, v185
	v_fmac_f32_dpp v179, v66, v102 row_shl:1 row_mask:0xf bank_mask:0xf
	v_fmac_f32_dpp v251, v66, v102 row_shr:15 row_mask:0xf bank_mask:0xf
	v_mov_b32_e32 v80, v251
	v_pk_fma_f32 v[252:253], v[114:115], v[82:83], v[126:127]
	v_mul_f32_e32 v84, 0xbfb8aa3b, v80
	v_exp_f32_e32 v84, v84
	v_fmac_f32_dpp v252, v82, v110 row_shr:1 row_mask:0xf bank_mask:0xf
	v_fmac_f32_dpp v253, v83, v111 row_shr:1 row_mask:0xf bank_mask:0xf
	v_add_f32_e32 v84, 1.0, v84
	v_fmac_f32_dpp v252, v170, v110 row_shl:15 row_mask:0xf bank_mask:0xf
	v_fmac_f32_dpp v253, v171, v111 row_shl:15 row_mask:0xf bank_mask:0xf
	v_rcp_f32_e32 v84, v84
	v_fmac_f32_dpp v252, v82, v122 row_shl:1 row_mask:0xf bank_mask:0xf
	v_fmac_f32_dpp v253, v83, v123 row_shl:1 row_mask:0xf bank_mask:0xf
	v_fmac_f32_dpp v179, v134, v102 row_shr:15 row_mask:0xf bank_mask:0xf
	v_fmac_f32_dpp v252, v70, v122 row_shr:15 row_mask:0xf bank_mask:0xf
	v_fmac_f32_dpp v253, v71, v123 row_shr:15 row_mask:0xf bank_mask:0xf
	v_mov_b32_e32 v66, v179
	v_fmac_f32_dpp v255, v69, v105 row_shl:1 row_mask:0xf bank_mask:0xf
	v_fmac_f32_dpp v250, v73, v113 row_shr:1 row_mask:0xf bank_mask:0xf
	v_add_u32_e32 v117, s93, v197
	v_fmac_f32_dpp v255, v137, v105 row_shr:15 row_mask:0xf bank_mask:0xf
	v_mov_b32_e32 v69, v255
	v_fma_f32 v181, v107, v81, v119
	v_fma_f32 v185, v107, v67, v119
	v_fmac_f32_dpp v250, v77, v113 row_shl:15 row_mask:0xf bank_mask:0xf
	v_fmac_f32_dpp v181, v81, v99 row_shr:1 row_mask:0xf bank_mask:0xf
	v_mov_b64_e32 v[76:77], v[248:249]
	v_pk_fma_f32 v[248:249], v[114:115], v[70:71], v[126:127]
	v_fmac_f32_dpp v181, v169, v99 row_shl:15 row_mask:0xf bank_mask:0xf
;     __device__ __forceinline__ void run(f32x4 (&acc)[2][2][4][2], const Unit& un, int wr, int wc, int fr, int fq, PG8_LAS unsigned char* xl) const {
;     ...
;                 const f32x4 w0g = *(const PG8_GAS f32x4*)(cw + j), w1g = *(const PG8_GAS f32x4*)(cw + nup + j), w2g = *(const PG8_GAS f32x4*)(cw + 2 * (size_t)nup + j), bg = *(const PG8_GAS f32x4*)(cb + j);
;                 const f32x4 w0v = *(const PG8_GAS f32x4*)(cw + dff + j), w1v = *(const PG8_GAS f32x4*)(cw + nup + dff + j), w2v = *(const PG8_GAS f32x4*)(cw + 2 * (size_t)nup + dff + j), bv = *(const PG8_GAS f32x4*)(cb + dff + j);
;                 f32x4 hpg, hpv, hng, hnv;
;                 if (blk > 0) { hpg = *(const PG8_LAS f32x4*)(X + ((blk - 1) * 2 + 1) * 256 + cl + 4 * n); hpv = *(const PG8_LAS f32x4*)(X + ((blk - 1) * 2 + 1) * 256 + 128 + cl + 4 * n); } else { hpg = (f32x4){0.f, 0.f, 0.f, 0.f}; hpv = hpg; }
;                 if (blk < 3) { hng = *(const PG8_LAS f32x4*)(X + ((blk + 1) * 2 + 0) * 256 + cl + 4 * n); hnv = *(const PG8_LAS f32x4*)(X + ((blk + 1) * 2 + 0) * 256 + 128 + cl + 4 * n); } else { hng = (f32x4){0.f, 0.f, 0.f, 0.f}; hnv = hng; }
; #pragma unroll
;                 for (int m = 0; m < 4; ++m) {
;                     float o[4];
; #pragma unroll
;                     for (int e = 0; e < 4; ++e) {
;                         const float g = acc[ai][0][m][n][e], v = acc[ai][1][m][n][e];
;                         const float gpe = m > 0 ? PG8_ROR1(acc[ai][0][m - 1][n][e]) : hpg[e], vpe = m > 0 ? PG8_ROR1(acc[ai][1][m - 1][n][e]) : hpv[e];
;                         const float gne = m < 3 ? PG8_ROR15(acc[ai][0][m + 1][n][e]) : hng[e], vne = m < 3 ? PG8_ROR15(acc[ai][1][m + 1][n][e]) : hnv[e];
;                         const float gpi = PG8_ROR1(g), vpi = PG8_ROR1(v), gni = PG8_ROR15(g), vni = PG8_ROR15(v);
;                         const float gp = e0 ? gpe : gpi, vp = e0 ? vpe : vpi, gn = e15 ? gne : gni, vn = e15 ? vne : vni;
;                         const float cg = fma_s(w2g[e], gn, fma_s(w1g[e], g, fma_s(w0g[e], gp, bg[e]))), cv = fma_s(w2v[e], vn, fma_s(w1v[e], v, fma_s(w0v[e], vp, bv[e])));
;                         o[e] = (cg * cv) * __builtin_amdgcn_rcpf(1.0f + __builtin_amdgcn_exp2f(cg * -1.4426950408889634f));
;                     }
;                     if (n == 0) { keep[m].x = cvt_pk_bf16(o[0], o[1]); keep[m].y = cvt_pk_bf16(o[2], o[3]); }
	v_pk_mul_f32 v[76:77], v[78:79], v[76:77]
	v_fmac_f32_dpp v248, v70, v110 row_shr:1 row_mask:0xf bank_mask:0xf
	v_fmac_f32_dpp v181, v81, v103 row_shl:1 row_mask:0xf bank_mask:0xf
	v_fmac_f32_dpp v249, v71, v111 row_shr:1 row_mask:0xf bank_mask:0xf
	v_fmac_f32_dpp v248, v82, v110 row_shl:15 row_mask:0xf bank_mask:0xf
	v_fmac_f32_dpp v181, v67, v103 row_shr:15 row_mask:0xf bank_mask:0xf
	v_fmac_f32_dpp v249, v83, v111 row_shl:15 row_mask:0xf bank_mask:0xf
	v_mov_b64_e32 v[82:83], v[252:253]
	v_fmac_f32_dpp v248, v70, v122 row_shl:1 row_mask:0xf bank_mask:0xf
	v_fmac_f32_dpp v249, v71, v123 row_shl:1 row_mask:0xf bank_mask:0xf
	v_fmac_f32_dpp v185, v67, v99 row_shr:1 row_mask:0xf bank_mask:0xf
	v_fmac_f32_dpp v248, v130, v122 row_shr:15 row_mask:0xf bank_mask:0xf
	v_fmac_f32_dpp v249, v131, v123 row_shr:15 row_mask:0xf bank_mask:0xf
	v_mov_b64_e32 v[70:71], v[248:249]
	v_fmac_f32_dpp v185, v81, v99 row_shl:15 row_mask:0xf bank_mask:0xf
	v_mov_b32_e32 v81, v181
	v_mul_f32_e32 v85, 0xbfb8aa3b, v81
	v_exp_f32_e32 v85, v85
	v_pk_mul_f32 v[80:81], v[80:81], v[82:83]
	v_add_f32_e32 v85, 1.0, v85
	v_rcp_f32_e32 v85, v85
	v_mul_f32_e32 v82, 0xbfb8aa3b, v78
	v_pk_mul_f32 v[80:81], v[80:81], v[84:85]
	v_exp_f32_e32 v82, v82
	v_mul_f32_e32 v83, 0xbfb8aa3b, v79
	v_exp_f32_e32 v83, v83
	v_add_f32_e32 v82, 1.0, v82
	v_rcp_f32_e32 v82, v82
	v_add_f32_e32 v83, 1.0, v83
	v_rcp_f32_e32 v83, v83
	v_cvt_pk_bf16_f32 v142, v80, v81
	v_pk_mul_f32 v[76:77], v[76:77], v[82:83]
	v_cvt_pk_bf16_f32 v143, v76, v77
	v_add_u32_e32 v76, 32, v172
	v_mad_i64_i32 v[76:77], s[14:15], v76, s5, v[74:75]
	v_lshl_add_u64 v[76:77], v[76:77], 0, v[146:147]
	global_store_dwordx4 v[76:77], v[140:143], off nt
	v_mul_f32_e32 v76, 0xbfb8aa3b, v66
	v_fmac_f32_dpp v185, v67, v103 row_shl:1 row_mask:0xf bank_mask:0xf
	v_exp_f32_e32 v76, v76
	v_fmac_f32_dpp v250, v73, v125 row_shl:1 row_mask:0xf bank_mask:0xf
	v_fmac_f32_dpp v185, v135, v103 row_shr:15 row_mask:0xf bank_mask:0xf
	v_mov_b32_e32 v67, v185
	v_mul_f32_e32 v77, 0xbfb8aa3b, v67
	v_exp_f32_e32 v77, v77
	v_add_f32_e32 v76, 1.0, v76
	v_rcp_f32_e32 v76, v76
	v_add_f32_e32 v77, 1.0, v77
	v_rcp_f32_e32 v77, v77
	v_pk_mul_f32 v[66:67], v[66:67], v[70:71]
	v_pk_mul_f32 v[66:67], v[66:67], v[76:77]
	v_mul_f32_e32 v71, 0xbfb8aa3b, v68
	v_exp_f32_e32 v71, v71
	v_mov_b32_e32 v70, v183
	v_add_f32_e32 v71, 1.0, v71
	v_rcp_f32_e32 v72, v71
	v_cvt_pk_bf16_f32 v140, v66, v67
	v_mul_f32_e32 v73, 0xbfb8aa3b, v69
	v_exp_f32_e32 v73, v73
	v_fmac_f32_dpp v250, v133, v125 row_shr:15 row_mask:0xf bank_mask:0xf
	v_mov_b32_e32 v71, v250
	v_add_u32_e32 v66, 48, v172
	v_pk_mul_f32 v[68:69], v[68:69], v[70:71]
	v_add_f32_e32 v73, 1.0, v73
	v_rcp_f32_e32 v73, v73
	v_mad_i64_i32 v[66:67], s[14:15], v66, s5, v[74:75]
	v_lshl_add_u64 v[66:67], v[66:67], 0, v[146:147]
	v_pk_mul_f32 v[68:69], v[68:69], v[72:73]
	v_cvt_pk_bf16_f32 v141, v68, v69
	global_store_dwordx4 v[66:67], v[138:141], off nt
	ds_read_b128 v[86:89], v247 offset:0
	ds_read_b128 v[82:85], v247 offset:512
	ds_read_b128 v[78:81], v247 offset:1024
	ds_read_b128 v[94:97], v247 offset:3072
	ds_read_b128 v[74:77], v247 offset:1536
	ds_read_b128 v[70:73], v247 offset:2048
	ds_read_b128 v[66:69], v247 offset:2560
	ds_read_b128 v[90:93], v247 offset:3584
	v_cndmask_b32_e64 v99, 0, 1, s[44:45]
	v_add_u32_e32 v115, s92, v197
	v_mov_b32_e32 v98, 0
	v_cmp_ne_u32_e64 s[14:15], 1, v99
	s_andn2_b64 vcc, exec, s[44:45]
	v_mov_b64_e32 v[106:107], 0
	v_mov_b64_e32 v[108:109], 0
	v_mov_b64_e32 v[110:111], 0
	v_mov_b64_e32 v[112:113], 0
	s_cbranch_vccnz .LBB0_804
	ds_read_b128 v[110:113], v117
	ds_read_b128 v[106:109], v115

; #define PG8_GAS __attribute__((address_space(1)))
; __device__ __forceinline__ unsigned cvt_pk_bf16(float lo, float hi) { const f32x2c v = {lo, hi}; return __builtin_bit_cast(unsigned, __builtin_convertvector(v, bf16x2c)); }
; __device__ __forceinline__ float fma_s(float a, float b, float c) { float d; asm("v_fma_f32 %0, %1, %2, %3" : "=v"(d) : "v"(a), "v"(b), "v"(c)); return d; }
; #define PG8_ROR1(x) dpp_ror1(x)
;     __device__ __forceinline__ void run(f32x4 (&acc)[2][2][4][2], const Unit& un, int wr, int wc, int fr, int fq, PG8_LAS unsigned char* xl) const {
;     ...
;             for (int m = 0; m < 4; ++m) { const float iv = __builtin_amdgcn_rsqf(ssq[(size_t)un.pm * BM + wr * 64 + fr + ai * HALF + m * 16] * inv_n + eps);
; #pragma unroll
;                 for (int bj = 0; bj < 2; ++bj)
; #pragma unroll
;                     for (int n = 0; n < 2; ++n) acc[ai][bj][m][n] = acc[ai][bj][m][n] * iv; }
;     ...
;                 for (int m = 0; m < 4; ++m) {
;                     float o[4];
; #pragma unroll
;                     for (int e = 0; e < 4; ++e) {
;                         const float g = acc[ai][0][m][n][e], v = acc[ai][1][m][n][e];
;                         const float gpe = m > 0 ? PG8_ROR1(acc[ai][0][m - 1][n][e]) : hpg[e], vpe = m > 0 ? PG8_ROR1(acc[ai][1][m - 1][n][e]) : hpv[e];
;                         const float gne = m < 3 ? PG8_ROR15(acc[ai][0][m + 1][n][e]) : hng[e], vne = m < 3 ? PG8_ROR15(acc[ai][1][m + 1][n][e]) : hnv[e];
;                         const float gpi = PG8_ROR1(g), vpi = PG8_ROR1(v), gni = PG8_ROR15(g), vni = PG8_ROR15(v);
;                         const float gp = e0 ? gpe : gpi, vp = e0 ? vpe : vpi, gn = e15 ? gne : gni, vn = e15 ? vne : vni;
;                         const float cg = fma_s(w2g[e], gn, fma_s(w1g[e], g, fma_s(w0g[e], gp, bg[e]))), cv = fma_s(w2v[e], vn, fma_s(w1v[e], v, fma_s(w0v[e], vp, bv[e])));
;                         o[e] = (cg * cv) * __builtin_amdgcn_rcpf(1.0f + __builtin_amdgcn_exp2f(cg * -1.4426950408889634f));
;                     }
;                     if (n == 0) { keep[m].x = cvt_pk_bf16(o[0], o[1]); keep[m].y = cvt_pk_bf16(o[2], o[3]); }
;                     else { u32x4 w; w.x = keep[m].x; w.y = keep[m].y; w.z = cvt_pk_bf16(o[0], o[1]); w.w = cvt_pk_bf16(o[2], o[3]);
;                         *(PG8_GAS u32x4*)(act + (size_t)(row0 + ai * HALF + m * 16) * dff + j - 4) = w; }
;                 }
.LBB0_810:
	v_mov_b32_e32 v115, v114
	v_mov_b32_e32 v117, v116
	v_mov_b32_e32 v84, v114
	v_mov_b32_e32 v85, v114
	v_pk_mul_f32 v[82:83], v[16:17], v[84:85]
	v_pk_mul_f32 v[86:87], v[14:15], v[114:115]
	v_pk_mul_f32 v[8:9], v[8:9], v[84:85]
	v_pk_mul_f32 v[84:85], v[6:7], v[114:115]
	v_mov_b32_e32 v6, v116
	v_mov_b32_e32 v7, v116
	v_pk_mul_f32 v[14:15], v[2:3], v[116:117]
	v_mul_f32_e32 v2, 0xbfb8aa3b, v88
	v_pk_mul_f32 v[16:17], v[10:11], v[116:117]
	v_pk_mul_f32 v[10:11], v[4:5], v[6:7]
	v_exp_f32_e32 v4, v2
	v_mul_f32_e32 v2, 0xbfb8aa3b, v89
	v_pk_mul_f32 v[12:13], v[12:13], v[6:7]
	v_exp_f32_e32 v5, v2
	v_mul_f32_e32 v6, 0xbfb8aa3b, v94
	v_mul_f32_e32 v7, 0xbfb8aa3b, v95
	v_exp_f32_e32 v6, v6
	v_exp_f32_e32 v7, v7
	v_add_f32_e32 v4, 1.0, v4
	v_add_f32_e32 v5, 1.0, v5
	v_rcp_f32_e32 v4, v4
	v_rcp_f32_e32 v5, v5
	v_add_f32_e32 v6, 1.0, v6
	v_add_f32_e32 v7, 1.0, v7
	v_rcp_f32_e32 v6, v6
	v_rcp_f32_e32 v7, v7
	v_pk_mul_f32 v[2:3], v[88:89], v[92:93]
	v_mul_f32_e32 v88, 0xbfb8aa3b, v126
	v_pk_mul_f32 v[2:3], v[2:3], v[4:5]
	v_pk_mul_f32 v[4:5], v[94:95], v[90:91]
	v_cvt_pk_bf16_f32 v3, v2, v3
	v_pk_mul_f32 v[4:5], v[4:5], v[6:7]
	v_mul_f32_e32 v89, 0xbfb8aa3b, v127
	v_cvt_pk_bf16_f32 v2, v4, v5
	v_mul_f32_e32 v4, 0xbfb8aa3b, v130
	v_exp_f32_e32 v6, v4
	v_mul_f32_e32 v4, 0xbfb8aa3b, v131
	v_exp_f32_e32 v7, v4
	v_exp_f32_e32 v88, v88
	v_exp_f32_e32 v89, v89
	v_add_f32_e32 v6, 1.0, v6
	v_add_f32_e32 v7, 1.0, v7
	v_rcp_f32_e32 v6, v6
	v_rcp_f32_e32 v7, v7
	v_add_f32_e32 v88, 1.0, v88
	v_add_f32_e32 v89, 1.0, v89
	v_rcp_f32_e32 v88, v88
	v_rcp_f32_e32 v89, v89
	v_pk_mul_f32 v[4:5], v[130:131], v[132:133]
	v_mul_f32_e32 v90, 0xbfb8aa3b, v118
	v_pk_mul_f32 v[4:5], v[4:5], v[6:7]
	v_pk_mul_f32 v[6:7], v[126:127], v[128:129]
	v_cvt_pk_bf16_f32 v5, v4, v5
	v_pk_mul_f32 v[6:7], v[6:7], v[88:89]
	v_mul_f32_e32 v91, 0xbfb8aa3b, v119
	v_cvt_pk_bf16_f32 v4, v6, v7
	v_mul_f32_e32 v6, 0xbfb8aa3b, v122
	v_exp_f32_e32 v88, v6
	v_mul_f32_e32 v6, 0xbfb8aa3b, v123
	v_exp_f32_e32 v89, v6
	v_exp_f32_e32 v90, v90
	v_exp_f32_e32 v91, v91
	v_add_f32_e32 v88, 1.0, v88
	v_add_f32_e32 v89, 1.0, v89
	v_rcp_f32_e32 v88, v88
	v_rcp_f32_e32 v89, v89
	v_add_f32_e32 v90, 1.0, v90
	v_add_f32_e32 v91, 1.0, v91
	v_rcp_f32_e32 v90, v90
	v_rcp_f32_e32 v91, v91
	v_pk_mul_f32 v[6:7], v[122:123], v[124:125]
	v_mul_f32_e32 v92, 0xbfb8aa3b, v106
	v_pk_mul_f32 v[6:7], v[6:7], v[88:89]
	v_pk_mul_f32 v[88:89], v[118:119], v[120:121]
	v_cvt_pk_bf16_f32 v7, v6, v7
	v_pk_mul_f32 v[88:89], v[88:89], v[90:91]
	v_mul_f32_e32 v93, 0xbfb8aa3b, v107
	v_cvt_pk_bf16_f32 v6, v88, v89
	v_mul_f32_e32 v88, 0xbfb8aa3b, v108
	v_exp_f32_e32 v90, v88
	v_mul_f32_e32 v88, 0xbfb8aa3b, v109
	v_exp_f32_e32 v91, v88
	v_exp_f32_e32 v92, v92
	v_exp_f32_e32 v93, v93
	v_add_f32_e32 v90, 1.0, v90
	v_add_f32_e32 v91, 1.0, v91
	v_rcp_f32_e32 v90, v90
	v_rcp_f32_e32 v91, v91
	v_add_f32_e32 v92, 1.0, v92
	v_add_f32_e32 v93, 1.0, v93
	v_rcp_f32_e32 v92, v92
	v_rcp_f32_e32 v93, v93
	v_pk_mul_f32 v[88:89], v[108:109], v[112:113]
	v_pk_mul_f32 v[88:89], v[88:89], v[90:91]
	v_pk_mul_f32 v[90:91], v[106:107], v[110:111]
	v_cvt_pk_bf16_f32 v89, v88, v89
	v_pk_mul_f32 v[90:91], v[90:91], v[92:93]
	v_cvt_pk_bf16_f32 v88, v90, v91
	s_waitcnt lgkmcnt(1)
	s_waitcnt lgkmcnt(0)
	s_waitcnt lgkmcnt(0)
	v_fma_f32 v179, v58, v38, v66
	s_waitcnt lgkmcnt(0)
	v_fma_f32 v255, v26, v46, v42
	v_fmac_f32_dpp v179, v38, v62 row_shr:1 row_mask:0xf bank_mask:0xf
	v_fma_f32 v181, v59, v39, v67
	v_fma_f32 v185, v27, v47, v43
	v_fmac_f32_dpp v179, v78, v62 row_shl:15 row_mask:0xf bank_mask:0xf
	v_fmac_f32_dpp v255, v46, v34 row_shr:1 row_mask:0xf bank_mask:0xf
	v_fmac_f32_dpp v181, v39, v63 row_shr:1 row_mask:0xf bank_mask:0xf
	v_fmac_f32_dpp v179, v38, v54 row_shl:1 row_mask:0xf bank_mask:0xf
	v_fmac_f32_dpp v255, v74, v34 row_shl:15 row_mask:0xf bank_mask:0xf
	v_fmac_f32_dpp v181, v79, v63 row_shl:15 row_mask:0xf bank_mask:0xf
	v_fmac_f32_dpp v179, v86, v54 row_shr:15 row_mask:0xf bank_mask:0xf
	v_mov_b32_e32 v74, v179
	v_mul_f32_e32 v78, 0xbfb8aa3b, v74
	v_exp_f32_e32 v94, v78
	v_fmac_f32_dpp v255, v46, v30 row_shl:1 row_mask:0xf bank_mask:0xf
	v_add_f32_e32 v90, 1.0, v94
	v_rcp_f32_e32 v90, v90
	v_fmac_f32_dpp v255, v84, v30 row_shr:15 row_mask:0xf bank_mask:0xf
	v_mov_b32_e32 v78, v255
	v_fmac_f32_dpp v181, v39, v55 row_shl:1 row_mask:0xf bank_mask:0xf
	v_fmac_f32_dpp v185, v47, v35 row_shr:1 row_mask:0xf bank_mask:0xf
	v_fma_f32 v183, v60, v40, v68
	v_fma_f32 v179, v28, v48, v44
	v_fmac_f32_dpp v181, v87, v55 row_shr:15 row_mask:0xf bank_mask:0xf
	v_fmac_f32_dpp v185, v75, v35 row_shl:15 row_mask:0xf bank_mask:0xf
	v_mov_b32_e32 v75, v181
	v_mul_f32_e32 v79, 0xbfb8aa3b, v75
	v_exp_f32_e32 v79, v79
	v_fmac_f32_dpp v185, v47, v31 row_shl:1 row_mask:0xf bank_mask:0xf
	v_add_f32_e32 v79, 1.0, v79
	v_rcp_f32_e32 v91, v79
	v_fmac_f32_dpp v185, v85, v31 row_shr:15 row_mask:0xf bank_mask:0xf
	v_mov_b32_e32 v79, v185
	v_pk_mul_f32 v[74:75], v[74:75], v[78:79]
	v_pk_mul_f32 v[74:75], v[74:75], v[90:91]
	v_fmac_f32_dpp v183, v40, v64 row_shr:1 row_mask:0xf bank_mask:0xf
	v_fmac_f32_dpp v179, v48, v36 row_shr:1 row_mask:0xf bank_mask:0xf
	v_fma_f32 v255, v61, v41, v69
	v_fma_f32 v181, v29, v49, v45
	v_fmac_f32_dpp v183, v80, v64 row_shl:15 row_mask:0xf bank_mask:0xf
	v_fmac_f32_dpp v179, v76, v36 row_shl:15 row_mask:0xf bank_mask:0xf
	v_fmac_f32_dpp v255, v41, v65 row_shr:1 row_mask:0xf bank_mask:0xf
	v_fmac_f32_dpp v183, v40, v56 row_shl:1 row_mask:0xf bank_mask:0xf
	v_fmac_f32_dpp v179, v48, v32 row_shl:1 row_mask:0xf bank_mask:0xf
	v_fmac_f32_dpp v255, v81, v65 row_shl:15 row_mask:0xf bank_mask:0xf
	v_fmac_f32_dpp v183, v82, v56 row_shr:15 row_mask:0xf bank_mask:0xf
; #define PG8_GAS __attribute__((address_space(1)))
; __device__ __forceinline__ unsigned cvt_pk_bf16(float lo, float hi) { const f32x2c v = {lo, hi}; return __builtin_bit_cast(unsigned, __builtin_convertvector(v, bf16x2c)); }
; __device__ __forceinline__ float fma_s(float a, float b, float c) { float d; asm("v_fma_f32 %0, %1, %2, %3" : "=v"(d) : "v"(a), "v"(b), "v"(c)); return d; }
; #define PG8_ROR1(x) dpp_ror1(x)
; #define PG8_ROR15(x) dpp_ror15(x)
;     __device__ __forceinline__ void run(f32x4 (&acc)[2][2][4][2], const Unit& un, int wr, int wc, int fr, int fq, PG8_LAS unsigned char* xl) const {
;     ...
;                 for (int m = 0; m < 4; ++m) {
;                     float o[4];
; #pragma unroll
;                     for (int e = 0; e < 4; ++e) {
;                         const float g = acc[ai][0][m][n][e], v = acc[ai][1][m][n][e];
;                         const float gpe = m > 0 ? PG8_ROR1(acc[ai][0][m - 1][n][e]) : hpg[e], vpe = m > 0 ? PG8_ROR1(acc[ai][1][m - 1][n][e]) : hpv[e];
;                         const float gne = m < 3 ? PG8_ROR15(acc[ai][0][m + 1][n][e]) : hng[e], vne = m < 3 ? PG8_ROR15(acc[ai][1][m + 1][n][e]) : hnv[e];
;                         const float gpi = PG8_ROR1(g), vpi = PG8_ROR1(v), gni = PG8_ROR15(g), vni = PG8_ROR15(v);
;                         const float gp = e0 ? gpe : gpi, vp = e0 ? vpe : vpi, gn = e15 ? gne : gni, vn = e15 ? vne : vni;
;                         const float cg = fma_s(w2g[e], gn, fma_s(w1g[e], g, fma_s(w0g[e], gp, bg[e]))), cv = fma_s(w2v[e], vn, fma_s(w1v[e], v, fma_s(w0v[e], vp, bv[e])));
;                         o[e] = (cg * cv) * __builtin_amdgcn_rcpf(1.0f + __builtin_amdgcn_exp2f(cg * -1.4426950408889634f));
;                     }
;                     if (n == 0) { keep[m].x = cvt_pk_bf16(o[0], o[1]); keep[m].y = cvt_pk_bf16(o[2], o[3]); }
;                     else { u32x4 w; w.x = keep[m].x; w.y = keep[m].y; w.z = cvt_pk_bf16(o[0], o[1]); w.w = cvt_pk_bf16(o[2], o[3]);
;                         *(PG8_GAS u32x4*)(act + (size_t)(row0 + ai * HALF + m * 16) * dff + j - 4) = w; }
;                 }
	v_mov_b32_e32 v76, v183
	v_mul_f32_e32 v78, 0xbfb8aa3b, v76
	v_exp_f32_e32 v90, v78
	v_fmac_f32_dpp v179, v8, v32 row_shr:15 row_mask:0xf bank_mask:0xf
	v_add_f32_e32 v79, 1.0, v90
	v_mov_b32_e32 v78, v179
	v_rcp_f32_e32 v80, v79
	v_fmac_f32_dpp v255, v41, v57 row_shl:1 row_mask:0xf bank_mask:0xf
	v_add_u32_e32 v92, 0x80, v172
	v_fmac_f32_dpp v181, v49, v37 row_shr:1 row_mask:0xf bank_mask:0xf
	v_fmac_f32_dpp v255, v83, v57 row_shr:15 row_mask:0xf bank_mask:0xf
	v_cvt_pk_bf16_f32 v90, v74, v75
	v_fmac_f32_dpp v181, v77, v37 row_shl:15 row_mask:0xf bank_mask:0xf
	v_mov_b32_e32 v77, v255
	v_mul_f32_e32 v79, 0xbfb8aa3b, v77
	v_exp_f32_e32 v79, v79
	v_fmac_f32_dpp v181, v49, v33 row_shl:1 row_mask:0xf bank_mask:0xf
	v_add_f32_e32 v79, 1.0, v79
	v_rcp_f32_e32 v81, v79
	v_fmac_f32_dpp v181, v9, v33 row_shr:15 row_mask:0xf bank_mask:0xf
	v_mov_b32_e32 v79, v181
	v_pk_mul_f32 v[76:77], v[76:77], v[78:79]
	v_pk_mul_f32 v[76:77], v[76:77], v[80:81]
	v_mov_b64_e32 v[74:75], s[24:25]
	v_cvt_pk_bf16_f32 v91, v76, v77
	v_mad_i64_i32 v[76:77], s[14:15], v92, s5, v[74:75]
	v_lshl_add_u64 v[76:77], v[76:77], 0, v[146:147]
	global_store_dwordx4 v[76:77], v[88:91], off nt
	v_pk_fma_f32 v[250:251], v[26:27], v[84:85], v[42:43]
	v_fma_f32 v185, v58, v86, v66
	v_fma_f32 v183, v59, v87, v67
	v_fmac_f32_dpp v250, v84, v34 row_shr:1 row_mask:0xf bank_mask:0xf
	v_fmac_f32_dpp v251, v85, v35 row_shr:1 row_mask:0xf bank_mask:0xf
	v_fmac_f32_dpp v185, v86, v62 row_shr:1 row_mask:0xf bank_mask:0xf
	v_fmac_f32_dpp v250, v46, v34 row_shl:15 row_mask:0xf bank_mask:0xf
	v_fmac_f32_dpp v251, v47, v35 row_shl:15 row_mask:0xf bank_mask:0xf
	v_fmac_f32_dpp v185, v38, v62 row_shl:15 row_mask:0xf bank_mask:0xf
	v_fmac_f32_dpp v250, v84, v30 row_shl:1 row_mask:0xf bank_mask:0xf
	v_fmac_f32_dpp v251, v85, v31 row_shl:1 row_mask:0xf bank_mask:0xf
	v_fmac_f32_dpp v185, v86, v54 row_shl:1 row_mask:0xf bank_mask:0xf
	v_fmac_f32_dpp v250, v14, v30 row_shr:15 row_mask:0xf bank_mask:0xf
	v_fmac_f32_dpp v251, v15, v31 row_shr:15 row_mask:0xf bank_mask:0xf
	v_mov_b64_e32 v[46:47], v[250:251]
	v_fmac_f32_dpp v185, v16, v54 row_shr:15 row_mask:0xf bank_mask:0xf
	v_mov_b32_e32 v38, v185
	v_mul_f32_e32 v76, 0xbfb8aa3b, v38
	v_fmac_f32_dpp v183, v87, v63 row_shr:1 row_mask:0xf bank_mask:0xf
	v_exp_f32_e32 v76, v76
	v_fma_f32 v179, v60, v82, v68
	v_fmac_f32_dpp v183, v39, v63 row_shl:15 row_mask:0xf bank_mask:0xf
	v_add_f32_e32 v76, 1.0, v76
	v_rcp_f32_e32 v76, v76
	v_fmac_f32_dpp v183, v87, v55 row_shl:1 row_mask:0xf bank_mask:0xf
	v_fmac_f32_dpp v179, v82, v64 row_shr:1 row_mask:0xf bank_mask:0xf
	v_pk_fma_f32 v[252:253], v[28:29], v[8:9], v[44:45]
	v_pk_fma_f32 v[248:249], v[28:29], v[10:11], v[44:45]
	v_pk_fma_f32 v[250:251], v[28:29], v[20:21], v[44:45]
	v_fmac_f32_dpp v183, v17, v55 row_shr:15 row_mask:0xf bank_mask:0xf
	v_mov_b32_e32 v39, v183
	v_mul_f32_e32 v77, 0xbfb8aa3b, v39
	v_exp_f32_e32 v77, v77
	v_pk_mul_f32 v[38:39], v[38:39], v[46:47]
	v_add_f32_e32 v77, 1.0, v77
	v_rcp_f32_e32 v77, v77
	v_fmac_f32_dpp v179, v40, v64 row_shl:15 row_mask:0xf bank_mask:0xf
	v_pk_mul_f32 v[38:39], v[38:39], v[76:77]
	v_fmac_f32_dpp v252, v8, v36 row_shr:1 row_mask:0xf bank_mask:0xf
	v_fmac_f32_dpp v179, v82, v56 row_shl:1 row_mask:0xf bank_mask:0xf
	v_fmac_f32_dpp v253, v9, v37 row_shr:1 row_mask:0xf bank_mask:0xf
	v_fmac_f32_dpp v252, v48, v36 row_shl:15 row_mask:0xf bank_mask:0xf
	v_fmac_f32_dpp v179, v12, v56 row_shr:15 row_mask:0xf bank_mask:0xf
	v_mov_b32_e32 v40, v179
	v_mul_f32_e32 v47, 0xbfb8aa3b, v40
	v_exp_f32_e32 v47, v47
	v_fmac_f32_dpp v253, v49, v37 row_shl:15 row_mask:0xf bank_mask:0xf
	v_add_f32_e32 v46, 1.0, v47
	v_fmac_f32_dpp v252, v8, v32 row_shl:1 row_mask:0xf bank_mask:0xf
	v_fmac_f32_dpp v253, v9, v33 row_shl:1 row_mask:0xf bank_mask:0xf
	v_fma_f32 v255, v61, v83, v69
	v_fmac_f32_dpp v252, v10, v32 row_shr:15 row_mask:0xf bank_mask:0xf
	v_fmac_f32_dpp v253, v11, v33 row_shr:15 row_mask:0xf bank_mask:0xf
	v_fmac_f32_dpp v255, v83, v65 row_shr:1 row_mask:0xf bank_mask:0xf
	v_rcp_f32_e32 v46, v46
	v_fmac_f32_dpp v248, v10, v36 row_shr:1 row_mask:0xf bank_mask:0xf
	v_fmac_f32_dpp v255, v41, v65 row_shl:15 row_mask:0xf bank_mask:0xf
	v_fmac_f32_dpp v249, v11, v37 row_shr:1 row_mask:0xf bank_mask:0xf
	v_fmac_f32_dpp v248, v8, v36 row_shl:15 row_mask:0xf bank_mask:0xf
	v_fmac_f32_dpp v255, v83, v57 row_shl:1 row_mask:0xf bank_mask:0xf
	v_fmac_f32_dpp v249, v9, v37 row_shl:15 row_mask:0xf bank_mask:0xf
	v_mov_b64_e32 v[8:9], v[252:253]
	v_fmac_f32_dpp v255, v13, v57 row_shr:15 row_mask:0xf bank_mask:0xf
	v_mov_b32_e32 v41, v255
	v_pk_mul_f32 v[8:9], v[40:41], v[8:9]
	v_fma_f32 v181, v58, v16, v66
	v_pk_fma_f32 v[252:253], v[26:27], v[14:15], v[42:43]
	v_fmac_f32_dpp v248, v10, v32 row_shl:1 row_mask:0xf bank_mask:0xf
	v_fmac_f32_dpp v181, v16, v62 row_shr:1 row_mask:0xf bank_mask:0xf
	v_fmac_f32_dpp v252, v14, v34 row_shr:1 row_mask:0xf bank_mask:0xf
	v_fmac_f32_dpp v253, v15, v35 row_shr:1 row_mask:0xf bank_mask:0xf
	v_fmac_f32_dpp v181, v86, v62 row_shl:15 row_mask:0xf bank_mask:0xf
	v_fmac_f32_dpp v252, v84, v34 row_shl:15 row_mask:0xf bank_mask:0xf
	v_fmac_f32_dpp v253, v85, v35 row_shl:15 row_mask:0xf bank_mask:0xf
	v_fmac_f32_dpp v181, v16, v54 row_shl:1 row_mask:0xf bank_mask:0xf
	v_fmac_f32_dpp v252, v14, v30 row_shl:1 row_mask:0xf bank_mask:0xf
	v_fmac_f32_dpp v253, v15, v31 row_shl:1 row_mask:0xf bank_mask:0xf
	v_fmac_f32_dpp v181, v22, v54 row_shr:15 row_mask:0xf bank_mask:0xf
	v_fmac_f32_dpp v252, v18, v30 row_shr:15 row_mask:0xf bank_mask:0xf
	v_fmac_f32_dpp v253, v19, v31 row_shr:15 row_mask:0xf bank_mask:0xf
	v_fmac_f32_dpp v249, v11, v33 row_shl:1 row_mask:0xf bank_mask:0xf
; #define PG8_GAS __attribute__((address_space(1)))
; __device__ __forceinline__ unsigned cvt_pk_bf16(float lo, float hi) { const f32x2c v = {lo, hi}; return __builtin_bit_cast(unsigned, __builtin_convertvector(v, bf16x2c)); }
; __device__ __forceinline__ float fma_s(float a, float b, float c) { float d; asm("v_fma_f32 %0, %1, %2, %3" : "=v"(d) : "v"(a), "v"(b), "v"(c)); return d; }
; #define PG8_ROR1(x) dpp_ror1(x)
; #define PG8_ROR15(x) dpp_ror15(x)
;     __device__ __forceinline__ void run(f32x4 (&acc)[2][2][4][2], const Unit& un, int wr, int wc, int fr, int fq, PG8_LAS unsigned char* xl) const {
;     ...
;                 for (int m = 0; m < 4; ++m) {
;                     float o[4];
; #pragma unroll
;                     for (int e = 0; e < 4; ++e) {
;                         const float g = acc[ai][0][m][n][e], v = acc[ai][1][m][n][e];
;                         const float gpe = m > 0 ? PG8_ROR1(acc[ai][0][m - 1][n][e]) : hpg[e], vpe = m > 0 ? PG8_ROR1(acc[ai][1][m - 1][n][e]) : hpv[e];
;                         const float gne = m < 3 ? PG8_ROR15(acc[ai][0][m + 1][n][e]) : hng[e], vne = m < 3 ? PG8_ROR15(acc[ai][1][m + 1][n][e]) : hnv[e];
;                         const float gpi = PG8_ROR1(g), vpi = PG8_ROR1(v), gni = PG8_ROR15(g), vni = PG8_ROR15(v);
;                         const float gp = e0 ? gpe : gpi, vp = e0 ? vpe : vpi, gn = e15 ? gne : gni, vn = e15 ? vne : vni;
;                         const float cg = fma_s(w2g[e], gn, fma_s(w1g[e], g, fma_s(w0g[e], gp, bg[e]))), cv = fma_s(w2v[e], vn, fma_s(w1v[e], v, fma_s(w0v[e], vp, bv[e])));
;                         o[e] = (cg * cv) * __builtin_amdgcn_rcpf(1.0f + __builtin_amdgcn_exp2f(cg * -1.4426950408889634f));
;                     }
;                     if (n == 0) { keep[m].x = cvt_pk_bf16(o[0], o[1]); keep[m].y = cvt_pk_bf16(o[2], o[3]); }
;                     else { u32x4 w; w.x = keep[m].x; w.y = keep[m].y; w.z = cvt_pk_bf16(o[0], o[1]); w.w = cvt_pk_bf16(o[2], o[3]);
;                         *(PG8_GAS u32x4*)(act + (size_t)(row0 + ai * HALF + m * 16) * dff + j - 4) = w; }
;                 }
	v_fmac_f32_dpp v248, v20, v32 row_shr:15 row_mask:0xf bank_mask:0xf
	v_fmac_f32_dpp v250, v20, v36 row_shr:1 row_mask:0xf bank_mask:0xf
	v_fmac_f32_dpp v249, v21, v33 row_shr:15 row_mask:0xf bank_mask:0xf
	v_fmac_f32_dpp v251, v21, v37 row_shr:1 row_mask:0xf bank_mask:0xf
	v_fmac_f32_dpp v250, v10, v36 row_shl:15 row_mask:0xf bank_mask:0xf
	v_fma_f32 v185, v59, v17, v67
	v_fmac_f32_dpp v251, v11, v37 row_shl:15 row_mask:0xf bank_mask:0xf
	v_mov_b64_e32 v[10:11], v[248:249]
	v_fmac_f32_dpp v185, v17, v63 row_shr:1 row_mask:0xf bank_mask:0xf
	v_fma_f32 v183, v60, v12, v68
	v_fmac_f32_dpp v250, v20, v32 row_shl:1 row_mask:0xf bank_mask:0xf
	v_fmac_f32_dpp v185, v87, v63 row_shl:15 row_mask:0xf bank_mask:0xf
	v_fmac_f32_dpp v183, v12, v64 row_shr:1 row_mask:0xf bank_mask:0xf
	v_fmac_f32_dpp v251, v21, v33 row_shl:1 row_mask:0xf bank_mask:0xf
	v_fmac_f32_dpp v185, v17, v55 row_shl:1 row_mask:0xf bank_mask:0xf
	v_fmac_f32_dpp v183, v82, v64 row_shl:15 row_mask:0xf bank_mask:0xf
	v_fmac_f32_dpp v250, v52, v32 row_shr:15 row_mask:0xf bank_mask:0xf
	v_fmac_f32_dpp v185, v23, v55 row_shr:15 row_mask:0xf bank_mask:0xf
	v_fmac_f32_dpp v183, v12, v56 row_shl:1 row_mask:0xf bank_mask:0xf
	v_fmac_f32_dpp v251, v53, v33 row_shr:15 row_mask:0xf bank_mask:0xf
	v_fma_f32 v179, v61, v13, v69
	v_fmac_f32_dpp v183, v24, v56 row_shr:15 row_mask:0xf bank_mask:0xf
	v_fma_f32 v255, v58, v22, v66
	v_fmac_f32_dpp v179, v13, v65 row_shr:1 row_mask:0xf bank_mask:0xf
	v_pk_fma_f32 v[248:249], v[26:27], v[18:19], v[42:43]
	v_fmac_f32_dpp v255, v22, v62 row_shr:1 row_mask:0xf bank_mask:0xf
	v_fmac_f32_dpp v179, v83, v65 row_shl:15 row_mask:0xf bank_mask:0xf
	v_mul_f32_e32 v83, 0xbfb8aa3b, v41
	v_exp_f32_e32 v83, v83
	v_fmac_f32_dpp v179, v13, v57 row_shl:1 row_mask:0xf bank_mask:0xf
	v_add_f32_e32 v47, 1.0, v83
	v_rcp_f32_e32 v47, v47
	v_fmac_f32_dpp v179, v25, v57 row_shr:15 row_mask:0xf bank_mask:0xf
	v_pk_mul_f32 v[40:41], v[8:9], v[46:47]
	v_cvt_pk_bf16_f32 v8, v38, v39
	v_add_u32_e32 v38, 0x90, v172
	v_mad_i64_i32 v[38:39], s[14:15], v38, s5, v[74:75]
	v_cvt_pk_bf16_f32 v9, v40, v41
	v_lshl_add_u64 v[38:39], v[38:39], 0, v[146:147]
	global_store_dwordx4 v[38:39], v[6:9], off nt
	v_fmac_f32_dpp v255, v16, v62 row_shl:15 row_mask:0xf bank_mask:0xf
	v_fmac_f32_dpp v248, v18, v34 row_shr:1 row_mask:0xf bank_mask:0xf
	v_mov_b32_e32 v6, v181
	v_mul_f32_e32 v8, 0xbfb8aa3b, v6
	v_exp_f32_e32 v16, v8
	v_mov_b64_e32 v[8:9], v[252:253]
	v_add_f32_e32 v7, 1.0, v16
	v_rcp_f32_e32 v16, v7
	v_mov_b32_e32 v7, v185
	v_fmac_f32_dpp v255, v22, v54 row_shl:1 row_mask:0xf bank_mask:0xf
	v_fmac_f32_dpp v249, v19, v35 row_shr:1 row_mask:0xf bank_mask:0xf
	v_fmac_f32_dpp v248, v14, v34 row_shl:15 row_mask:0xf bank_mask:0xf
	v_fmac_f32_dpp v255, v70, v54 row_shr:15 row_mask:0xf bank_mask:0xf
	v_fmac_f32_dpp v249, v15, v35 row_shl:15 row_mask:0xf bank_mask:0xf
	v_fmac_f32_dpp v248, v18, v30 row_shl:1 row_mask:0xf bank_mask:0xf
	v_fma_f32 v181, v59, v23, v67
	v_fmac_f32_dpp v249, v19, v31 row_shl:1 row_mask:0xf bank_mask:0xf
	v_fmac_f32_dpp v248, v50, v30 row_shr:15 row_mask:0xf bank_mask:0xf
	v_fmac_f32_dpp v181, v23, v63 row_shr:1 row_mask:0xf bank_mask:0xf
	v_fmac_f32_dpp v249, v51, v31 row_shr:15 row_mask:0xf bank_mask:0xf
	v_fma_f32 v185, v60, v24, v68
	v_fmac_f32_dpp v181, v17, v63 row_shl:15 row_mask:0xf bank_mask:0xf
	v_mul_f32_e32 v17, 0xbfb8aa3b, v7
	v_exp_f32_e32 v17, v17
	v_pk_mul_f32 v[6:7], v[6:7], v[8:9]
	v_add_f32_e32 v17, 1.0, v17
	v_rcp_f32_e32 v17, v17
	v_mov_b32_e32 v8, v183
	v_pk_mul_f32 v[6:7], v[6:7], v[16:17]
	v_cvt_pk_bf16_f32 v6, v6, v7
	v_fmac_f32_dpp v181, v23, v55 row_shl:1 row_mask:0xf bank_mask:0xf
	v_fmac_f32_dpp v185, v24, v64 row_shr:1 row_mask:0xf bank_mask:0xf
	v_fma_f32 v183, v61, v25, v69
	v_fmac_f32_dpp v181, v71, v55 row_shr:15 row_mask:0xf bank_mask:0xf
	v_fmac_f32_dpp v185, v12, v64 row_shl:15 row_mask:0xf bank_mask:0xf
	v_mul_f32_e32 v12, 0xbfb8aa3b, v8
	v_exp_f32_e32 v12, v12
	v_fmac_f32_dpp v185, v24, v56 row_shl:1 row_mask:0xf bank_mask:0xf
	v_add_f32_e32 v9, 1.0, v12
	v_rcp_f32_e32 v12, v9
	v_mov_b32_e32 v9, v179
	v_fmac_f32_dpp v185, v72, v56 row_shr:15 row_mask:0xf bank_mask:0xf
	v_fmac_f32_dpp v183, v25, v65 row_shr:1 row_mask:0xf bank_mask:0xf
	s_nop 0
	s_nop 0
	v_fmac_f32_dpp v183, v13, v65 row_shl:15 row_mask:0xf bank_mask:0xf
	v_mul_f32_e32 v13, 0xbfb8aa3b, v9
	v_exp_f32_e32 v13, v13
	v_pk_mul_f32 v[8:9], v[8:9], v[10:11]
	v_add_f32_e32 v13, 1.0, v13
	v_rcp_f32_e32 v13, v13
	v_fmac_f32_dpp v183, v25, v57 row_shl:1 row_mask:0xf bank_mask:0xf
	v_pk_mul_f32 v[8:9], v[8:9], v[12:13]
	v_cvt_pk_bf16_f32 v7, v8, v9
	v_add_u32_e32 v8, 0xa0, v172
	v_mad_i64_i32 v[8:9], s[14:15], v8, s5, v[74:75]
	v_lshl_add_u64 v[8:9], v[8:9], 0, v[146:147]
	global_store_dwordx4 v[8:9], v[4:7], off nt
	v_fmac_f32_dpp v183, v73, v57 row_shr:15 row_mask:0xf bank_mask:0xf
	s_nop 0
	v_mov_b32_e32 v4, v255
	v_mul_f32_e32 v6, 0xbfb8aa3b, v4
	v_exp_f32_e32 v8, v6
	v_mov_b64_e32 v[6:7], v[248:249]
	v_add_f32_e32 v5, 1.0, v8
	v_rcp_f32_e32 v8, v5
	v_mov_b32_e32 v5, v181
	v_mul_f32_e32 v9, 0xbfb8aa3b, v5
	v_exp_f32_e32 v9, v9
	v_pk_mul_f32 v[4:5], v[4:5], v[6:7]
	v_add_f32_e32 v9, 1.0, v9
	v_rcp_f32_e32 v9, v9
	v_mov_b32_e32 v6, v185
	v_pk_mul_f32 v[4:5], v[4:5], v[8:9]
	v_mul_f32_e32 v8, 0xbfb8aa3b, v6
	v_exp_f32_e32 v10, v8
	v_mov_b64_e32 v[8:9], v[250:251]
	v_add_f32_e32 v7, 1.0, v10
	v_rcp_f32_e32 v10, v7
	v_cvt_pk_bf16_f32 v4, v4, v5
	v_mov_b32_e32 v7, v183
	v_mul_f32_e32 v11, 0xbfb8aa3b, v7
	v_exp_f32_e32 v11, v11
	v_pk_mul_f32 v[6:7], v[6:7], v[8:9]
	v_add_f32_e32 v11, 1.0, v11
	v_rcp_f32_e32 v11, v11
	s_nop 0
	v_pk_mul_f32 v[6:7], v[6:7], v[10:11]
	v_cvt_pk_bf16_f32 v5, v6, v7
	v_add_u32_e32 v6, 0xb0, v172
	v_mad_i64_i32 v[6:7], s[10:11], v6, s5, v[74:75]
	v_lshl_add_u64 v[6:7], v[6:7], 0, v[146:147]
	global_store_dwordx4 v[6:7], v[2:5], off nt
	v_mov_b32_e32 v179, 0
	v_mov_b32_e32 v181, 0
	v_mov_b32_e32 v183, 0
	v_mov_b32_e32 v185, 0
	s_andn2_b64 vcc, exec, s[8:9]
	s_mov_b64 s[8:9], -1
	s_cbranch_vccnz .LBB0_766
	s_andn2_b64 vcc, exec, s[30:31]
	s_cbranch_vccnz .LBB0_765
	s_barrier
	s_branch .LBB0_765
